# P3 scan: per-token instruction order re-derived (first partial-sum add gets a private register) so the two DPP reduction chains need no s_nop padding: 41 nops removed per 32-token chunk
# speedup vs baseline: 1.0119x; 1.0119x over previous
; __device__ __forceinline__ void rwkv_scan_prompt(const Params& p, LAS unsigned char* lds, int bh, int rq) {
;     ...
;     for (int c = 0; c < NCH; ++c) {
;         const int buf = c & 1;
;         if (wave >= 4) {
;             if (c + 1 < NCH) store_chunk(buf ^ 1);
;             if (c + 2 < NCH) issue_chunk(c + 2);
;         } else {
;             float yk[TC / 16];
; #pragma unroll
;             for (int j = 0; j < TC / 16; ++j) yk[j] = 0.f;
;             const LAS float* ob = OPS + buf * TC * 6 * 64;
;             f32x4 r4 = *(const LAS f32x4*)(ob + cg_ * 4), d4 = *(const LAS f32x4*)(ob + 64 + cg_ * 4), k4 = *(const LAS f32x4*)(ob + 128 + cg_ * 4),
;                   a4 = *(const LAS f32x4*)(ob + 256 + cg_ * 4), b4 = *(const LAS f32x4*)(ob + 320 + cg_ * 4);
;             float vv = ob[192 + rq * 16 + rloc];
;             f32x4 rp = r4;
; #pragma unroll
;             for (int tk = 0; tk < TC; ++tk) {
;                 f32x4 nr4 = r4, nd4 = d4, nk4 = k4, na4 = a4, nb4 = b4; float nvv = vv;
;                 if (tk < TC - 1) {
;                     const LAS float* o = ob + (tk + 1) * 6 * 64;
;                     nr4 = *(const LAS f32x4*)(o + cg_ * 4); nd4 = *(const LAS f32x4*)(o + 64 + cg_ * 4); nk4 = *(const LAS f32x4*)(o + 128 + cg_ * 4);
;                     na4 = *(const LAS f32x4*)(o + 256 + cg_ * 4); nb4 = *(const LAS f32x4*)(o + 320 + cg_ * 4);
;                     nvv = o[192 + rq * 16 + rloc];
;                 }
;                 __builtin_amdgcn_sched_barrier(0);
;                 typedef float f32x2_ __attribute__((ext_vector_type(2)));
;                 f32x2_ ta = (f32x2_){S[0], S[1]} * (f32x2_){a4[0], a4[1]}; ta = (f32x2_){S[2], S[3]} * (f32x2_){a4[2], a4[3]} + ta;
;                 f32x2_ ty = (f32x2_){S[0], S[1]} * (f32x2_){rp[0], rp[1]}; ty = (f32x2_){S[2], S[3]} * (f32x2_){rp[2], rp[3]} + ty;
;                 const f32x4 T = S * d4 + vv * k4;
;                 float sa = ta[0] + ta[1];
;                 float yp = ty[0] + ty[1];
;                 sa = dpp_add<0xB1>(sa); yp = dpp_add<0xB1>(yp);
;                 sa = dpp_add<0x4E>(sa); yp = dpp_add<0x4E>(yp);
;                 sa = dpp_add<0x124>(sa); yp = dpp_add<0x124>(yp);
;                 sa = dpp_add<0x128>(sa); yp = dpp_add<0x128>(yp);
;                 if (tk > 0) yk[(tk - 1) >> 4] = (cg_ == ((tk - 1) & 15)) ? yp : yk[(tk - 1) >> 4];
;                 S = sa * b4 + T;
.LBB0_336:
	s_and_b32 s95, s73, 1
	s_and_saveexec_b64 s[74:75], s[38:39]
	s_xor_b64 s[74:75], exec, s[74:75]
	s_cbranch_execz .LBB0_338
	s_mul_i32 s78, s95, 0xc000
	s_add_i32 s78, s78, 0
	v_lshl_add_u32 v28, v36, 2, s78
	v_lshl_add_u32 v29, v154, 2, s78
	ds_read_b128 v[30:33], v28
	ds_read_b128 v[160:163], v28 offset:256
	ds_read_b128 v[164:167], v28 offset:512
	ds_read_b128 v[168:171], v28 offset:1024
	ds_read2st64_b32 v[34:35], v29 offset0:3 offset1:9
	ds_read_b128 v[172:175], v28 offset:1280
	ds_read_b128 v[176:179], v28 offset:1536
	ds_read_b128 v[180:183], v28 offset:1792
	ds_read_b128 v[184:187], v28 offset:2048
	ds_read_b128 v[188:191], v28 offset:2560
	ds_read_b128 v[192:195], v28 offset:2816
	s_waitcnt lgkmcnt(7)
	v_pk_mul_f32 v[170:171], v[26:27], v[170:171]
	s_waitcnt lgkmcnt(6)
	v_pk_mul_f32 v[164:165], v[164:165], v[34:35] op_sel_hi:[1,0]
	v_pk_fma_f32 v[168:169], v[24:25], v[168:169], v[170:171]
	v_pk_mul_f32 v[166:167], v[166:167], v[34:35] op_sel_hi:[1,0]
	v_add_f32_e32 v168, v168, v169
	v_pk_fma_f32 v[26:27], v[26:27], v[162:163], v[166:167]
	v_pk_fma_f32 v[24:25], v[24:25], v[160:161], v[164:165]
	v_add_f32_dpp v168, v168, v168 quad_perm:[1,0,3,2] row_mask:0xf bank_mask:0xf bound_ctrl:1
	s_nop 1
	v_add_f32_dpp v168, v168, v168 quad_perm:[2,3,0,1] row_mask:0xf bank_mask:0xf bound_ctrl:1
	s_nop 1
	v_add_f32_dpp v168, v168, v168 row_ror:4 row_mask:0xf bank_mask:0xf bound_ctrl:1
	s_nop 1
	v_add_f32_dpp v168, v168, v168 row_ror:8 row_mask:0xf bank_mask:0xf bound_ctrl:1
	s_waitcnt lgkmcnt(5)
	v_pk_fma_f32 v[196:197], v[172:173], v[168:169], v[24:25] op_sel_hi:[1,0,1]
	v_pk_fma_f32 v[198:199], v[174:175], v[168:169], v[26:27] op_sel_hi:[1,0,1]
	ds_read_b128 v[24:27], v28 offset:3072
	ds_read_b128 v[160:163], v28 offset:3328
	ds_read_b128 v[164:167], v28 offset:3584
	ds_read_b128 v[168:171], v28 offset:4096
	ds_read_b128 v[172:175], v28 offset:4352
	ds_read_b32 v34, v29 offset:3840
	s_waitcnt lgkmcnt(7)
	v_pk_mul_f32 v[190:191], v[190:191], v[198:199]
	v_pk_mul_f32 v[32:33], v[32:33], v[198:199]
	v_pk_fma_f32 v[188:189], v[188:189], v[196:197], v[190:191]
	v_pk_fma_f32 v[30:31], v[30:31], v[196:197], v[32:33]
	v_pk_mul_f32 v[32:33], v[180:181], v[196:197]
	v_add_f32_e32 v206, v188, v189
	v_pk_mul_f32 v[180:181], v[182:183], v[198:199]
	v_add_f32_e32 v30, v30, v31
	v_add_f32_dpp v31, v206, v206 quad_perm:[1,0,3,2] row_mask:0xf bank_mask:0xf bound_ctrl:1
	v_mov_b32_e32 v182, v35
	v_add_f32_dpp v30, v30, v30 quad_perm:[1,0,3,2] row_mask:0xf bank_mask:0xf bound_ctrl:1
	v_add_f32_dpp v31, v31, v31 quad_perm:[2,3,0,1] row_mask:0xf bank_mask:0xf bound_ctrl:1
	v_pk_fma_f32 v[180:181], v[186:187], v[182:183], v[180:181] op_sel_hi:[1,0,1]
	v_add_f32_dpp v30, v30, v30 quad_perm:[2,3,0,1] row_mask:0xf bank_mask:0xf bound_ctrl:1
	v_add_f32_dpp v31, v31, v31 row_ror:4 row_mask:0xf bank_mask:0xf bound_ctrl:1
	v_pk_fma_f32 v[32:33], v[184:185], v[182:183], v[32:33] op_sel_hi:[1,0,1]
	v_add_f32_dpp v35, v30, v30 row_ror:4 row_mask:0xf bank_mask:0xf bound_ctrl:1
	v_add_f32_dpp v30, v31, v31 row_ror:8 row_mask:0xf bank_mask:0xf bound_ctrl:1
	s_waitcnt lgkmcnt(6)
	v_pk_fma_f32 v[196:197], v[192:193], v[30:31], v[32:33] op_sel_hi:[1,0,1]
	v_add_f32_dpp v31, v35, v35 row_ror:8 row_mask:0xf bank_mask:0xf bound_ctrl:1
	v_cndmask_b32_e64 v201, 0, v31, s[6:7]
	v_pk_fma_f32 v[198:199], v[194:195], v[30:31], v[180:181] op_sel_hi:[1,0,1]
	ds_read_b128 v[30:33], v28 offset:4608
	ds_read_b128 v[180:183], v28 offset:4864
	ds_read_b128 v[184:187], v28 offset:5120
	ds_read_b128 v[188:191], v28 offset:5632
	ds_read_b128 v[192:195], v28 offset:5888
	ds_read_b32 v200, v29 offset:5376
	s_waitcnt lgkmcnt(8)
	v_pk_mul_f32 v[170:171], v[170:171], v[198:199]
	v_pk_mul_f32 v[160:161], v[160:161], v[196:197]
	v_pk_fma_f32 v[168:169], v[168:169], v[196:197], v[170:171]
	v_pk_mul_f32 v[170:171], v[178:179], v[198:199]
	v_pk_mul_f32 v[162:163], v[162:163], v[198:199]
	v_pk_fma_f32 v[170:171], v[176:177], v[196:197], v[170:171]
	s_waitcnt lgkmcnt(6)
	v_pk_fma_f32 v[162:163], v[166:167], v[34:35], v[162:163] op_sel_hi:[1,0,1]
	v_add_f32_e32 v206, v168, v169
	v_pk_fma_f32 v[34:35], v[164:165], v[34:35], v[160:161] op_sel_hi:[1,0,1]
	v_add_f32_e32 v161, v170, v171
	v_add_f32_dpp v160, v206, v206 quad_perm:[1,0,3,2] row_mask:0xf bank_mask:0xf bound_ctrl:1
	s_nop 0
	v_add_f32_dpp v161, v161, v161 quad_perm:[1,0,3,2] row_mask:0xf bank_mask:0xf bound_ctrl:1
	v_add_f32_dpp v160, v160, v160 quad_perm:[2,3,0,1] row_mask:0xf bank_mask:0xf bound_ctrl:1
	s_nop 0
	v_add_f32_dpp v161, v161, v161 quad_perm:[2,3,0,1] row_mask:0xf bank_mask:0xf bound_ctrl:1
	v_add_f32_dpp v160, v160, v160 row_ror:4 row_mask:0xf bank_mask:0xf bound_ctrl:1
	s_nop 0
	v_add_f32_dpp v161, v161, v161 row_ror:4 row_mask:0xf bank_mask:0xf bound_ctrl:1
	v_add_f32_dpp v160, v160, v160 row_ror:8 row_mask:0xf bank_mask:0xf bound_ctrl:1
	v_pk_fma_f32 v[34:35], v[172:173], v[160:161], v[34:35] op_sel_hi:[1,0,1]
	v_add_f32_dpp v161, v161, v161 row_ror:8 row_mask:0xf bank_mask:0xf bound_ctrl:1
	v_cndmask_b32_e64 v199, v201, v161, s[8:9]
	v_pk_fma_f32 v[196:197], v[174:175], v[160:161], v[162:163] op_sel_hi:[1,0,1]
	ds_read_b128 v[160:163], v28 offset:6144
	ds_read_b128 v[164:167], v28 offset:6400
	ds_read_b128 v[168:171], v28 offset:6656
	ds_read_b128 v[172:175], v28 offset:7168
	ds_read_b128 v[176:179], v28 offset:7424
	ds_read_b32 v198, v29 offset:6912
	s_waitcnt lgkmcnt(8)
; #define LAS __attribute__((address_space(3)))
; __device__ __forceinline__ void rwkv_scan_prompt(const Params& p, LAS unsigned char* lds, int bh, int rq) {
;     ...
;             for (int tk = 0; tk < TC; ++tk) {
;                 f32x4 nr4 = r4, nd4 = d4, nk4 = k4, na4 = a4, nb4 = b4; float nvv = vv;
;                 if (tk < TC - 1) {
;                     const LAS float* o = ob + (tk + 1) * 6 * 64;
;                     nr4 = *(const LAS f32x4*)(o + cg_ * 4); nd4 = *(const LAS f32x4*)(o + 64 + cg_ * 4); nk4 = *(const LAS f32x4*)(o + 128 + cg_ * 4);
;                     na4 = *(const LAS f32x4*)(o + 256 + cg_ * 4); nb4 = *(const LAS f32x4*)(o + 320 + cg_ * 4);
;                     nvv = o[192 + rq * 16 + rloc];
;                 }
;                 __builtin_amdgcn_sched_barrier(0);
;                 typedef float f32x2_ __attribute__((ext_vector_type(2)));
;                 f32x2_ ta = (f32x2_){S[0], S[1]} * (f32x2_){a4[0], a4[1]}; ta = (f32x2_){S[2], S[3]} * (f32x2_){a4[2], a4[3]} + ta;
;                 f32x2_ ty = (f32x2_){S[0], S[1]} * (f32x2_){rp[0], rp[1]}; ty = (f32x2_){S[2], S[3]} * (f32x2_){rp[2], rp[3]} + ty;
;                 const f32x4 T = S * d4 + vv * k4;
;                 float sa = ta[0] + ta[1];
;                 float yp = ty[0] + ty[1];
;                 sa = dpp_add<0xB1>(sa); yp = dpp_add<0xB1>(yp);
;                 sa = dpp_add<0x4E>(sa); yp = dpp_add<0x4E>(yp);
;                 sa = dpp_add<0x124>(sa); yp = dpp_add<0x124>(yp);
;                 sa = dpp_add<0x128>(sa); yp = dpp_add<0x128>(yp);
;                 if (tk > 0) yk[(tk - 1) >> 4] = (cg_ == ((tk - 1) & 15)) ? yp : yk[(tk - 1) >> 4];
;                 S = sa * b4 + T;
;                 rp = r4;
;                 r4 = nr4; d4 = nd4; k4 = nk4; a4 = na4; b4 = nb4; vv = nvv;
	v_pk_mul_f32 v[190:191], v[190:191], v[196:197]
	v_pk_mul_f32 v[26:27], v[26:27], v[196:197]
	v_pk_fma_f32 v[188:189], v[188:189], v[34:35], v[190:191]
	v_pk_fma_f32 v[24:25], v[24:25], v[34:35], v[26:27]
	v_add_f32_e32 v206, v188, v189
	v_pk_mul_f32 v[26:27], v[180:181], v[34:35]
	v_add_f32_e32 v24, v24, v25
	v_add_f32_dpp v25, v206, v206 quad_perm:[1,0,3,2] row_mask:0xf bank_mask:0xf bound_ctrl:1
	v_pk_mul_f32 v[34:35], v[182:183], v[196:197]
	v_add_f32_dpp v24, v24, v24 quad_perm:[1,0,3,2] row_mask:0xf bank_mask:0xf bound_ctrl:1
	s_waitcnt lgkmcnt(6)
	v_add_f32_dpp v25, v25, v25 quad_perm:[2,3,0,1] row_mask:0xf bank_mask:0xf bound_ctrl:1
	v_pk_fma_f32 v[34:35], v[186:187], v[200:201], v[34:35] op_sel_hi:[1,0,1]
	v_add_f32_dpp v24, v24, v24 quad_perm:[2,3,0,1] row_mask:0xf bank_mask:0xf bound_ctrl:1
	v_add_f32_dpp v25, v25, v25 row_ror:4 row_mask:0xf bank_mask:0xf bound_ctrl:1
	v_pk_fma_f32 v[26:27], v[184:185], v[200:201], v[26:27] op_sel_hi:[1,0,1]
	v_add_f32_dpp v180, v24, v24 row_ror:4 row_mask:0xf bank_mask:0xf bound_ctrl:1
	v_add_f32_dpp v24, v25, v25 row_ror:8 row_mask:0xf bank_mask:0xf bound_ctrl:1
	v_pk_fma_f32 v[196:197], v[192:193], v[24:25], v[26:27] op_sel_hi:[1,0,1]
	v_add_f32_dpp v25, v180, v180 row_ror:8 row_mask:0xf bank_mask:0xf bound_ctrl:1
	v_cndmask_b32_e64 v199, v199, v25, s[10:11]
	v_pk_fma_f32 v[34:35], v[194:195], v[24:25], v[34:35] op_sel_hi:[1,0,1]
	ds_read_b128 v[24:27], v28 offset:7680
	ds_read_b128 v[180:183], v28 offset:7936
	ds_read_b128 v[184:187], v28 offset:8192
	ds_read_b128 v[188:191], v28 offset:8704
	ds_read_b128 v[192:195], v28 offset:8960
	ds_read_b32 v200, v29 offset:8448
	s_waitcnt lgkmcnt(8)
	v_pk_mul_f32 v[174:175], v[174:175], v[34:35]
	v_pk_mul_f32 v[32:33], v[32:33], v[34:35]
	v_pk_fma_f32 v[172:173], v[172:173], v[196:197], v[174:175]
	v_pk_fma_f32 v[30:31], v[30:31], v[196:197], v[32:33]
	v_add_f32_e32 v206, v172, v173
	v_pk_mul_f32 v[32:33], v[164:165], v[196:197]
	v_add_f32_e32 v30, v30, v31
	v_add_f32_dpp v31, v206, v206 quad_perm:[1,0,3,2] row_mask:0xf bank_mask:0xf bound_ctrl:1
	v_pk_mul_f32 v[34:35], v[166:167], v[34:35]
	v_add_f32_dpp v30, v30, v30 quad_perm:[1,0,3,2] row_mask:0xf bank_mask:0xf bound_ctrl:1
	s_waitcnt lgkmcnt(6)
	v_add_f32_dpp v31, v31, v31 quad_perm:[2,3,0,1] row_mask:0xf bank_mask:0xf bound_ctrl:1
	v_pk_fma_f32 v[34:35], v[170:171], v[198:199], v[34:35] op_sel_hi:[1,0,1]
	v_add_f32_dpp v30, v30, v30 quad_perm:[2,3,0,1] row_mask:0xf bank_mask:0xf bound_ctrl:1
	v_add_f32_dpp v31, v31, v31 row_ror:4 row_mask:0xf bank_mask:0xf bound_ctrl:1
	v_pk_fma_f32 v[32:33], v[168:169], v[198:199], v[32:33] op_sel_hi:[1,0,1]
	v_add_f32_dpp v164, v30, v30 row_ror:4 row_mask:0xf bank_mask:0xf bound_ctrl:1
	v_add_f32_dpp v30, v31, v31 row_ror:8 row_mask:0xf bank_mask:0xf bound_ctrl:1
	v_pk_fma_f32 v[196:197], v[176:177], v[30:31], v[32:33] op_sel_hi:[1,0,1]
	v_add_f32_dpp v31, v164, v164 row_ror:8 row_mask:0xf bank_mask:0xf bound_ctrl:1
	v_cndmask_b32_e64 v199, v199, v31, s[12:13]
	v_pk_fma_f32 v[34:35], v[178:179], v[30:31], v[34:35] op_sel_hi:[1,0,1]
	ds_read_b128 v[30:33], v28 offset:9216
	ds_read_b128 v[164:167], v28 offset:9472
	ds_read_b128 v[168:171], v28 offset:9728
	ds_read_b128 v[172:175], v28 offset:10240
	ds_read_b128 v[176:179], v28 offset:10496
	ds_read_b32 v198, v29 offset:9984
	s_waitcnt lgkmcnt(8)
	v_pk_mul_f32 v[190:191], v[190:191], v[34:35]
	v_pk_mul_f32 v[162:163], v[162:163], v[34:35]
	v_pk_fma_f32 v[188:189], v[188:189], v[196:197], v[190:191]
	v_pk_fma_f32 v[160:161], v[160:161], v[196:197], v[162:163]
	v_add_f32_e32 v206, v188, v189
	v_pk_mul_f32 v[162:163], v[180:181], v[196:197]
	v_add_f32_e32 v160, v160, v161
	v_add_f32_dpp v161, v206, v206 quad_perm:[1,0,3,2] row_mask:0xf bank_mask:0xf bound_ctrl:1
	v_pk_mul_f32 v[34:35], v[182:183], v[34:35]
	v_add_f32_dpp v160, v160, v160 quad_perm:[1,0,3,2] row_mask:0xf bank_mask:0xf bound_ctrl:1
	s_waitcnt lgkmcnt(6)
	v_add_f32_dpp v161, v161, v161 quad_perm:[2,3,0,1] row_mask:0xf bank_mask:0xf bound_ctrl:1
	v_pk_fma_f32 v[34:35], v[186:187], v[200:201], v[34:35] op_sel_hi:[1,0,1]
	v_add_f32_dpp v160, v160, v160 quad_perm:[2,3,0,1] row_mask:0xf bank_mask:0xf bound_ctrl:1
	v_add_f32_dpp v161, v161, v161 row_ror:4 row_mask:0xf bank_mask:0xf bound_ctrl:1
	v_pk_fma_f32 v[162:163], v[184:185], v[200:201], v[162:163] op_sel_hi:[1,0,1]
	v_add_f32_dpp v180, v160, v160 row_ror:4 row_mask:0xf bank_mask:0xf bound_ctrl:1
	v_add_f32_dpp v160, v161, v161 row_ror:8 row_mask:0xf bank_mask:0xf bound_ctrl:1
	v_pk_fma_f32 v[196:197], v[192:193], v[160:161], v[162:163] op_sel_hi:[1,0,1]
	v_add_f32_dpp v161, v180, v180 row_ror:8 row_mask:0xf bank_mask:0xf bound_ctrl:1
	v_cndmask_b32_e64 v199, v199, v161, s[14:15]
	v_pk_fma_f32 v[34:35], v[194:195], v[160:161], v[34:35] op_sel_hi:[1,0,1]
	ds_read_b128 v[160:163], v28 offset:10752
	ds_read_b128 v[180:183], v28 offset:11008
	ds_read_b128 v[184:187], v28 offset:11264
	ds_read_b128 v[188:191], v28 offset:11776
	ds_read_b128 v[192:195], v28 offset:12032
	ds_read_b32 v200, v29 offset:11520
	s_waitcnt lgkmcnt(8)
	v_pk_mul_f32 v[174:175], v[174:175], v[34:35]
	v_pk_mul_f32 v[26:27], v[26:27], v[34:35]
	v_pk_fma_f32 v[172:173], v[172:173], v[196:197], v[174:175]
	v_pk_fma_f32 v[24:25], v[24:25], v[196:197], v[26:27]
	v_add_f32_e32 v206, v172, v173
	v_pk_mul_f32 v[26:27], v[164:165], v[196:197]
	v_add_f32_e32 v24, v24, v25
	v_add_f32_dpp v25, v206, v206 quad_perm:[1,0,3,2] row_mask:0xf bank_mask:0xf bound_ctrl:1
	v_pk_mul_f32 v[34:35], v[166:167], v[34:35]
	v_add_f32_dpp v24, v24, v24 quad_perm:[1,0,3,2] row_mask:0xf bank_mask:0xf bound_ctrl:1
	s_waitcnt lgkmcnt(6)
; #define LAS __attribute__((address_space(3)))
; __device__ __forceinline__ void rwkv_scan_prompt(const Params& p, LAS unsigned char* lds, int bh, int rq) {
;     ...
;             for (int tk = 0; tk < TC; ++tk) {
;                 f32x4 nr4 = r4, nd4 = d4, nk4 = k4, na4 = a4, nb4 = b4; float nvv = vv;
;                 if (tk < TC - 1) {
;                     const LAS float* o = ob + (tk + 1) * 6 * 64;
;                     nr4 = *(const LAS f32x4*)(o + cg_ * 4); nd4 = *(const LAS f32x4*)(o + 64 + cg_ * 4); nk4 = *(const LAS f32x4*)(o + 128 + cg_ * 4);
;                     na4 = *(const LAS f32x4*)(o + 256 + cg_ * 4); nb4 = *(const LAS f32x4*)(o + 320 + cg_ * 4);
;                     nvv = o[192 + rq * 16 + rloc];
;                 }
;                 __builtin_amdgcn_sched_barrier(0);
;                 typedef float f32x2_ __attribute__((ext_vector_type(2)));
;                 f32x2_ ta = (f32x2_){S[0], S[1]} * (f32x2_){a4[0], a4[1]}; ta = (f32x2_){S[2], S[3]} * (f32x2_){a4[2], a4[3]} + ta;
;                 f32x2_ ty = (f32x2_){S[0], S[1]} * (f32x2_){rp[0], rp[1]}; ty = (f32x2_){S[2], S[3]} * (f32x2_){rp[2], rp[3]} + ty;
;                 const f32x4 T = S * d4 + vv * k4;
;                 float sa = ta[0] + ta[1];
;                 float yp = ty[0] + ty[1];
;                 sa = dpp_add<0xB1>(sa); yp = dpp_add<0xB1>(yp);
;                 sa = dpp_add<0x4E>(sa); yp = dpp_add<0x4E>(yp);
;                 sa = dpp_add<0x124>(sa); yp = dpp_add<0x124>(yp);
;                 sa = dpp_add<0x128>(sa); yp = dpp_add<0x128>(yp);
;                 if (tk > 0) yk[(tk - 1) >> 4] = (cg_ == ((tk - 1) & 15)) ? yp : yk[(tk - 1) >> 4];
;                 S = sa * b4 + T;
;                 rp = r4;
;                 r4 = nr4; d4 = nd4; k4 = nk4; a4 = na4; b4 = nb4; vv = nvv;
	v_add_f32_dpp v25, v25, v25 quad_perm:[2,3,0,1] row_mask:0xf bank_mask:0xf bound_ctrl:1
	v_pk_fma_f32 v[34:35], v[170:171], v[198:199], v[34:35] op_sel_hi:[1,0,1]
	v_add_f32_dpp v24, v24, v24 quad_perm:[2,3,0,1] row_mask:0xf bank_mask:0xf bound_ctrl:1
	v_add_f32_dpp v25, v25, v25 row_ror:4 row_mask:0xf bank_mask:0xf bound_ctrl:1
	v_pk_fma_f32 v[26:27], v[168:169], v[198:199], v[26:27] op_sel_hi:[1,0,1]
	v_add_f32_dpp v164, v24, v24 row_ror:4 row_mask:0xf bank_mask:0xf bound_ctrl:1
	v_add_f32_dpp v24, v25, v25 row_ror:8 row_mask:0xf bank_mask:0xf bound_ctrl:1
	v_pk_fma_f32 v[196:197], v[176:177], v[24:25], v[26:27] op_sel_hi:[1,0,1]
	v_add_f32_dpp v25, v164, v164 row_ror:8 row_mask:0xf bank_mask:0xf bound_ctrl:1
	v_cndmask_b32_e64 v199, v199, v25, s[16:17]
	v_pk_fma_f32 v[34:35], v[178:179], v[24:25], v[34:35] op_sel_hi:[1,0,1]
	ds_read_b128 v[24:27], v28 offset:12288
	ds_read_b128 v[164:167], v28 offset:12544
	ds_read_b128 v[168:171], v28 offset:12800
	ds_read_b128 v[172:175], v28 offset:13312
	ds_read_b128 v[176:179], v28 offset:13568
	ds_read_b32 v198, v29 offset:13056
	s_waitcnt lgkmcnt(8)
	v_pk_mul_f32 v[190:191], v[190:191], v[34:35]
	v_pk_mul_f32 v[32:33], v[32:33], v[34:35]
	v_pk_fma_f32 v[188:189], v[188:189], v[196:197], v[190:191]
	v_pk_fma_f32 v[30:31], v[30:31], v[196:197], v[32:33]
	v_add_f32_e32 v206, v188, v189
	v_pk_mul_f32 v[32:33], v[180:181], v[196:197]
	v_add_f32_e32 v30, v30, v31
	v_add_f32_dpp v31, v206, v206 quad_perm:[1,0,3,2] row_mask:0xf bank_mask:0xf bound_ctrl:1
	v_pk_mul_f32 v[34:35], v[182:183], v[34:35]
	v_add_f32_dpp v30, v30, v30 quad_perm:[1,0,3,2] row_mask:0xf bank_mask:0xf bound_ctrl:1
	s_waitcnt lgkmcnt(6)
	v_add_f32_dpp v31, v31, v31 quad_perm:[2,3,0,1] row_mask:0xf bank_mask:0xf bound_ctrl:1
	v_pk_fma_f32 v[34:35], v[186:187], v[200:201], v[34:35] op_sel_hi:[1,0,1]
	v_add_f32_dpp v30, v30, v30 quad_perm:[2,3,0,1] row_mask:0xf bank_mask:0xf bound_ctrl:1
	v_add_f32_dpp v31, v31, v31 row_ror:4 row_mask:0xf bank_mask:0xf bound_ctrl:1
	v_pk_fma_f32 v[32:33], v[184:185], v[200:201], v[32:33] op_sel_hi:[1,0,1]
	v_add_f32_dpp v180, v30, v30 row_ror:4 row_mask:0xf bank_mask:0xf bound_ctrl:1
	v_add_f32_dpp v30, v31, v31 row_ror:8 row_mask:0xf bank_mask:0xf bound_ctrl:1
	v_pk_fma_f32 v[196:197], v[192:193], v[30:31], v[32:33] op_sel_hi:[1,0,1]
	v_add_f32_dpp v31, v180, v180 row_ror:8 row_mask:0xf bank_mask:0xf bound_ctrl:1
	v_cndmask_b32_e64 v199, v199, v31, s[18:19]
	v_pk_fma_f32 v[34:35], v[194:195], v[30:31], v[34:35] op_sel_hi:[1,0,1]
	ds_read_b128 v[30:33], v28 offset:13824
	ds_read_b128 v[180:183], v28 offset:14080
	ds_read_b128 v[184:187], v28 offset:14336
	ds_read_b128 v[188:191], v28 offset:14848
	ds_read_b128 v[192:195], v28 offset:15104
	ds_read_b32 v200, v29 offset:14592
	s_waitcnt lgkmcnt(8)
	v_pk_mul_f32 v[174:175], v[174:175], v[34:35]
	v_pk_mul_f32 v[162:163], v[162:163], v[34:35]
	v_pk_fma_f32 v[172:173], v[172:173], v[196:197], v[174:175]
	v_pk_fma_f32 v[160:161], v[160:161], v[196:197], v[162:163]
	v_add_f32_e32 v206, v172, v173
	v_pk_mul_f32 v[162:163], v[164:165], v[196:197]
	v_add_f32_e32 v160, v160, v161
	v_add_f32_dpp v161, v206, v206 quad_perm:[1,0,3,2] row_mask:0xf bank_mask:0xf bound_ctrl:1
	v_pk_mul_f32 v[34:35], v[166:167], v[34:35]
	v_add_f32_dpp v160, v160, v160 quad_perm:[1,0,3,2] row_mask:0xf bank_mask:0xf bound_ctrl:1
	s_waitcnt lgkmcnt(6)
	v_add_f32_dpp v161, v161, v161 quad_perm:[2,3,0,1] row_mask:0xf bank_mask:0xf bound_ctrl:1
	v_pk_fma_f32 v[34:35], v[170:171], v[198:199], v[34:35] op_sel_hi:[1,0,1]
	v_add_f32_dpp v160, v160, v160 quad_perm:[2,3,0,1] row_mask:0xf bank_mask:0xf bound_ctrl:1
	v_add_f32_dpp v161, v161, v161 row_ror:4 row_mask:0xf bank_mask:0xf bound_ctrl:1
	v_pk_fma_f32 v[162:163], v[168:169], v[198:199], v[162:163] op_sel_hi:[1,0,1]
	v_add_f32_dpp v164, v160, v160 row_ror:4 row_mask:0xf bank_mask:0xf bound_ctrl:1
	v_add_f32_dpp v160, v161, v161 row_ror:8 row_mask:0xf bank_mask:0xf bound_ctrl:1
	v_pk_fma_f32 v[196:197], v[176:177], v[160:161], v[162:163] op_sel_hi:[1,0,1]
	v_add_f32_dpp v161, v164, v164 row_ror:8 row_mask:0xf bank_mask:0xf bound_ctrl:1
	v_cndmask_b32_e64 v199, v199, v161, s[20:21]
	v_pk_fma_f32 v[34:35], v[178:179], v[160:161], v[34:35] op_sel_hi:[1,0,1]
	ds_read_b128 v[160:163], v28 offset:15360
	ds_read_b128 v[164:167], v28 offset:15616
	ds_read_b128 v[168:171], v28 offset:15872
	ds_read_b128 v[172:175], v28 offset:16384
	ds_read_b128 v[176:179], v28 offset:16640
	ds_read_b32 v198, v29 offset:16128
	s_waitcnt lgkmcnt(8)
	v_pk_mul_f32 v[190:191], v[190:191], v[34:35]
	v_pk_mul_f32 v[26:27], v[26:27], v[34:35]
	v_pk_fma_f32 v[188:189], v[188:189], v[196:197], v[190:191]
	v_pk_fma_f32 v[24:25], v[24:25], v[196:197], v[26:27]
	v_add_f32_e32 v206, v188, v189
	v_pk_mul_f32 v[26:27], v[180:181], v[196:197]
	v_add_f32_e32 v24, v24, v25
	v_add_f32_dpp v25, v206, v206 quad_perm:[1,0,3,2] row_mask:0xf bank_mask:0xf bound_ctrl:1
	v_pk_mul_f32 v[34:35], v[182:183], v[34:35]
	v_add_f32_dpp v24, v24, v24 quad_perm:[1,0,3,2] row_mask:0xf bank_mask:0xf bound_ctrl:1
	s_waitcnt lgkmcnt(6)
	v_add_f32_dpp v25, v25, v25 quad_perm:[2,3,0,1] row_mask:0xf bank_mask:0xf bound_ctrl:1
	v_pk_fma_f32 v[34:35], v[186:187], v[200:201], v[34:35] op_sel_hi:[1,0,1]
	v_add_f32_dpp v24, v24, v24 quad_perm:[2,3,0,1] row_mask:0xf bank_mask:0xf bound_ctrl:1
	v_add_f32_dpp v25, v25, v25 row_ror:4 row_mask:0xf bank_mask:0xf bound_ctrl:1
	v_pk_fma_f32 v[26:27], v[184:185], v[200:201], v[26:27] op_sel_hi:[1,0,1]
	v_add_f32_dpp v180, v24, v24 row_ror:4 row_mask:0xf bank_mask:0xf bound_ctrl:1
	v_add_f32_dpp v24, v25, v25 row_ror:8 row_mask:0xf bank_mask:0xf bound_ctrl:1
	v_pk_fma_f32 v[196:197], v[192:193], v[24:25], v[26:27] op_sel_hi:[1,0,1]
	v_add_f32_dpp v25, v180, v180 row_ror:8 row_mask:0xf bank_mask:0xf bound_ctrl:1
	v_cndmask_b32_e64 v199, v199, v25, s[22:23]
	v_pk_fma_f32 v[34:35], v[194:195], v[24:25], v[34:35] op_sel_hi:[1,0,1]
	ds_read_b128 v[24:27], v28 offset:16896
	ds_read_b128 v[180:183], v28 offset:17152
	ds_read_b128 v[184:187], v28 offset:17408
	ds_read_b128 v[188:191], v28 offset:17920
	ds_read_b128 v[192:195], v28 offset:18176
	ds_read_b32 v200, v29 offset:17664
	s_waitcnt lgkmcnt(8)
; #define LAS __attribute__((address_space(3)))
; __device__ __forceinline__ void rwkv_scan_prompt(const Params& p, LAS unsigned char* lds, int bh, int rq) {
;     ...
;             for (int tk = 0; tk < TC; ++tk) {
;                 f32x4 nr4 = r4, nd4 = d4, nk4 = k4, na4 = a4, nb4 = b4; float nvv = vv;
;                 if (tk < TC - 1) {
;                     const LAS float* o = ob + (tk + 1) * 6 * 64;
;                     nr4 = *(const LAS f32x4*)(o + cg_ * 4); nd4 = *(const LAS f32x4*)(o + 64 + cg_ * 4); nk4 = *(const LAS f32x4*)(o + 128 + cg_ * 4);
;                     na4 = *(const LAS f32x4*)(o + 256 + cg_ * 4); nb4 = *(const LAS f32x4*)(o + 320 + cg_ * 4);
;                     nvv = o[192 + rq * 16 + rloc];
;                 }
;                 __builtin_amdgcn_sched_barrier(0);
;                 typedef float f32x2_ __attribute__((ext_vector_type(2)));
;                 f32x2_ ta = (f32x2_){S[0], S[1]} * (f32x2_){a4[0], a4[1]}; ta = (f32x2_){S[2], S[3]} * (f32x2_){a4[2], a4[3]} + ta;
;                 f32x2_ ty = (f32x2_){S[0], S[1]} * (f32x2_){rp[0], rp[1]}; ty = (f32x2_){S[2], S[3]} * (f32x2_){rp[2], rp[3]} + ty;
;                 const f32x4 T = S * d4 + vv * k4;
;                 float sa = ta[0] + ta[1];
;                 float yp = ty[0] + ty[1];
;                 sa = dpp_add<0xB1>(sa); yp = dpp_add<0xB1>(yp);
;                 sa = dpp_add<0x4E>(sa); yp = dpp_add<0x4E>(yp);
;                 sa = dpp_add<0x124>(sa); yp = dpp_add<0x124>(yp);
;                 sa = dpp_add<0x128>(sa); yp = dpp_add<0x128>(yp);
;                 if (tk > 0) yk[(tk - 1) >> 4] = (cg_ == ((tk - 1) & 15)) ? yp : yk[(tk - 1) >> 4];
;                 S = sa * b4 + T;
;                 rp = r4;
;                 r4 = nr4; d4 = nd4; k4 = nk4; a4 = na4; b4 = nb4; vv = nvv;
	v_pk_mul_f32 v[174:175], v[174:175], v[34:35]
	v_pk_mul_f32 v[32:33], v[32:33], v[34:35]
	v_pk_fma_f32 v[172:173], v[172:173], v[196:197], v[174:175]
	v_pk_fma_f32 v[30:31], v[30:31], v[196:197], v[32:33]
	v_add_f32_e32 v206, v172, v173
	v_pk_mul_f32 v[32:33], v[164:165], v[196:197]
	v_add_f32_e32 v30, v30, v31
	v_add_f32_dpp v31, v206, v206 quad_perm:[1,0,3,2] row_mask:0xf bank_mask:0xf bound_ctrl:1
	v_pk_mul_f32 v[34:35], v[166:167], v[34:35]
	v_add_f32_dpp v30, v30, v30 quad_perm:[1,0,3,2] row_mask:0xf bank_mask:0xf bound_ctrl:1
	s_waitcnt lgkmcnt(6)
	v_add_f32_dpp v31, v31, v31 quad_perm:[2,3,0,1] row_mask:0xf bank_mask:0xf bound_ctrl:1
	v_pk_fma_f32 v[34:35], v[170:171], v[198:199], v[34:35] op_sel_hi:[1,0,1]
	v_add_f32_dpp v30, v30, v30 quad_perm:[2,3,0,1] row_mask:0xf bank_mask:0xf bound_ctrl:1
	v_add_f32_dpp v31, v31, v31 row_ror:4 row_mask:0xf bank_mask:0xf bound_ctrl:1
	v_pk_fma_f32 v[32:33], v[168:169], v[198:199], v[32:33] op_sel_hi:[1,0,1]
	v_add_f32_dpp v164, v30, v30 row_ror:4 row_mask:0xf bank_mask:0xf bound_ctrl:1
	v_add_f32_dpp v30, v31, v31 row_ror:8 row_mask:0xf bank_mask:0xf bound_ctrl:1
	v_pk_fma_f32 v[196:197], v[176:177], v[30:31], v[32:33] op_sel_hi:[1,0,1]
	v_add_f32_dpp v31, v164, v164 row_ror:8 row_mask:0xf bank_mask:0xf bound_ctrl:1
	v_cndmask_b32_e64 v199, v199, v31, s[24:25]
	v_pk_fma_f32 v[34:35], v[178:179], v[30:31], v[34:35] op_sel_hi:[1,0,1]
	ds_read_b128 v[30:33], v28 offset:18432
	ds_read_b128 v[164:167], v28 offset:18688
	ds_read_b128 v[168:171], v28 offset:18944
	ds_read_b128 v[172:175], v28 offset:19456
	ds_read_b128 v[176:179], v28 offset:19712
	ds_read_b32 v198, v29 offset:19200
	s_waitcnt lgkmcnt(8)
	v_pk_mul_f32 v[190:191], v[190:191], v[34:35]
	v_pk_mul_f32 v[162:163], v[162:163], v[34:35]
	v_pk_fma_f32 v[188:189], v[188:189], v[196:197], v[190:191]
	v_pk_fma_f32 v[160:161], v[160:161], v[196:197], v[162:163]
	v_add_f32_e32 v206, v188, v189
	v_pk_mul_f32 v[162:163], v[180:181], v[196:197]
	v_add_f32_e32 v160, v160, v161
	v_add_f32_dpp v161, v206, v206 quad_perm:[1,0,3,2] row_mask:0xf bank_mask:0xf bound_ctrl:1
	v_pk_mul_f32 v[34:35], v[182:183], v[34:35]
	v_add_f32_dpp v160, v160, v160 quad_perm:[1,0,3,2] row_mask:0xf bank_mask:0xf bound_ctrl:1
	s_waitcnt lgkmcnt(6)
	v_add_f32_dpp v161, v161, v161 quad_perm:[2,3,0,1] row_mask:0xf bank_mask:0xf bound_ctrl:1
	v_pk_fma_f32 v[34:35], v[186:187], v[200:201], v[34:35] op_sel_hi:[1,0,1]
	v_add_f32_dpp v160, v160, v160 quad_perm:[2,3,0,1] row_mask:0xf bank_mask:0xf bound_ctrl:1
	v_add_f32_dpp v161, v161, v161 row_ror:4 row_mask:0xf bank_mask:0xf bound_ctrl:1
	v_pk_fma_f32 v[162:163], v[184:185], v[200:201], v[162:163] op_sel_hi:[1,0,1]
	v_add_f32_dpp v180, v160, v160 row_ror:4 row_mask:0xf bank_mask:0xf bound_ctrl:1
	v_add_f32_dpp v160, v161, v161 row_ror:8 row_mask:0xf bank_mask:0xf bound_ctrl:1
	v_pk_fma_f32 v[196:197], v[192:193], v[160:161], v[162:163] op_sel_hi:[1,0,1]
	v_add_f32_dpp v161, v180, v180 row_ror:8 row_mask:0xf bank_mask:0xf bound_ctrl:1
	v_cndmask_b32_e64 v199, v199, v161, s[26:27]
	v_pk_fma_f32 v[34:35], v[194:195], v[160:161], v[34:35] op_sel_hi:[1,0,1]
	ds_read_b128 v[160:163], v28 offset:19968
	ds_read_b128 v[180:183], v28 offset:20224
	ds_read_b128 v[184:187], v28 offset:20480
	ds_read_b128 v[188:191], v28 offset:20992
	ds_read_b128 v[192:195], v28 offset:21248
	ds_read_b32 v200, v29 offset:20736
	s_waitcnt lgkmcnt(8)
	v_pk_mul_f32 v[174:175], v[174:175], v[34:35]
	v_pk_mul_f32 v[26:27], v[26:27], v[34:35]
	v_pk_fma_f32 v[172:173], v[172:173], v[196:197], v[174:175]
	v_pk_fma_f32 v[24:25], v[24:25], v[196:197], v[26:27]
	v_add_f32_e32 v206, v172, v173
	v_pk_mul_f32 v[26:27], v[164:165], v[196:197]
	v_add_f32_e32 v24, v24, v25
	v_add_f32_dpp v25, v206, v206 quad_perm:[1,0,3,2] row_mask:0xf bank_mask:0xf bound_ctrl:1
	v_pk_mul_f32 v[34:35], v[166:167], v[34:35]
	v_add_f32_dpp v24, v24, v24 quad_perm:[1,0,3,2] row_mask:0xf bank_mask:0xf bound_ctrl:1
	s_waitcnt lgkmcnt(6)
	v_add_f32_dpp v25, v25, v25 quad_perm:[2,3,0,1] row_mask:0xf bank_mask:0xf bound_ctrl:1
	v_pk_fma_f32 v[34:35], v[170:171], v[198:199], v[34:35] op_sel_hi:[1,0,1]
	v_add_f32_dpp v24, v24, v24 quad_perm:[2,3,0,1] row_mask:0xf bank_mask:0xf bound_ctrl:1
	v_add_f32_dpp v25, v25, v25 row_ror:4 row_mask:0xf bank_mask:0xf bound_ctrl:1
	v_pk_fma_f32 v[26:27], v[168:169], v[198:199], v[26:27] op_sel_hi:[1,0,1]
	v_add_f32_dpp v164, v24, v24 row_ror:4 row_mask:0xf bank_mask:0xf bound_ctrl:1
	v_add_f32_dpp v24, v25, v25 row_ror:8 row_mask:0xf bank_mask:0xf bound_ctrl:1
	v_pk_fma_f32 v[196:197], v[176:177], v[24:25], v[26:27] op_sel_hi:[1,0,1]
	v_add_f32_dpp v25, v164, v164 row_ror:8 row_mask:0xf bank_mask:0xf bound_ctrl:1
	v_cndmask_b32_e64 v199, v199, v25, s[28:29]
	v_pk_fma_f32 v[34:35], v[178:179], v[24:25], v[34:35] op_sel_hi:[1,0,1]
	ds_read_b128 v[24:27], v28 offset:21504
	ds_read_b128 v[164:167], v28 offset:21760
	ds_read_b128 v[168:171], v28 offset:22016
	ds_read_b128 v[172:175], v28 offset:22528
	ds_read_b128 v[176:179], v28 offset:22784
	ds_read_b32 v198, v29 offset:22272
	s_waitcnt lgkmcnt(8)
	v_pk_mul_f32 v[190:191], v[190:191], v[34:35]
	v_pk_mul_f32 v[32:33], v[32:33], v[34:35]
	v_pk_fma_f32 v[188:189], v[188:189], v[196:197], v[190:191]
	v_pk_fma_f32 v[30:31], v[30:31], v[196:197], v[32:33]
	v_add_f32_e32 v206, v188, v189
	v_pk_mul_f32 v[32:33], v[180:181], v[196:197]
	v_add_f32_e32 v30, v30, v31
	v_add_f32_dpp v31, v206, v206 quad_perm:[1,0,3,2] row_mask:0xf bank_mask:0xf bound_ctrl:1
	v_pk_mul_f32 v[34:35], v[182:183], v[34:35]
	v_add_f32_dpp v30, v30, v30 quad_perm:[1,0,3,2] row_mask:0xf bank_mask:0xf bound_ctrl:1
	s_waitcnt lgkmcnt(6)
; #define LAS __attribute__((address_space(3)))
; __device__ __forceinline__ void rwkv_scan_prompt(const Params& p, LAS unsigned char* lds, int bh, int rq) {
;     ...
;             for (int tk = 0; tk < TC; ++tk) {
;                 f32x4 nr4 = r4, nd4 = d4, nk4 = k4, na4 = a4, nb4 = b4; float nvv = vv;
;                 if (tk < TC - 1) {
;                     const LAS float* o = ob + (tk + 1) * 6 * 64;
;                     nr4 = *(const LAS f32x4*)(o + cg_ * 4); nd4 = *(const LAS f32x4*)(o + 64 + cg_ * 4); nk4 = *(const LAS f32x4*)(o + 128 + cg_ * 4);
;                     na4 = *(const LAS f32x4*)(o + 256 + cg_ * 4); nb4 = *(const LAS f32x4*)(o + 320 + cg_ * 4);
;                     nvv = o[192 + rq * 16 + rloc];
;                 }
;                 __builtin_amdgcn_sched_barrier(0);
;                 typedef float f32x2_ __attribute__((ext_vector_type(2)));
;                 f32x2_ ta = (f32x2_){S[0], S[1]} * (f32x2_){a4[0], a4[1]}; ta = (f32x2_){S[2], S[3]} * (f32x2_){a4[2], a4[3]} + ta;
;                 f32x2_ ty = (f32x2_){S[0], S[1]} * (f32x2_){rp[0], rp[1]}; ty = (f32x2_){S[2], S[3]} * (f32x2_){rp[2], rp[3]} + ty;
;                 const f32x4 T = S * d4 + vv * k4;
;                 float sa = ta[0] + ta[1];
;                 float yp = ty[0] + ty[1];
;                 sa = dpp_add<0xB1>(sa); yp = dpp_add<0xB1>(yp);
;                 sa = dpp_add<0x4E>(sa); yp = dpp_add<0x4E>(yp);
;                 sa = dpp_add<0x124>(sa); yp = dpp_add<0x124>(yp);
;                 sa = dpp_add<0x128>(sa); yp = dpp_add<0x128>(yp);
;                 if (tk > 0) yk[(tk - 1) >> 4] = (cg_ == ((tk - 1) & 15)) ? yp : yk[(tk - 1) >> 4];
;                 S = sa * b4 + T;
;                 rp = r4;
;                 r4 = nr4; d4 = nd4; k4 = nk4; a4 = na4; b4 = nb4; vv = nvv;
	v_add_f32_dpp v31, v31, v31 quad_perm:[2,3,0,1] row_mask:0xf bank_mask:0xf bound_ctrl:1
	v_pk_fma_f32 v[34:35], v[186:187], v[200:201], v[34:35] op_sel_hi:[1,0,1]
	v_add_f32_dpp v30, v30, v30 quad_perm:[2,3,0,1] row_mask:0xf bank_mask:0xf bound_ctrl:1
	v_add_f32_dpp v31, v31, v31 row_ror:4 row_mask:0xf bank_mask:0xf bound_ctrl:1
	v_pk_fma_f32 v[32:33], v[184:185], v[200:201], v[32:33] op_sel_hi:[1,0,1]
	v_add_f32_dpp v180, v30, v30 row_ror:4 row_mask:0xf bank_mask:0xf bound_ctrl:1
	v_add_f32_dpp v30, v31, v31 row_ror:8 row_mask:0xf bank_mask:0xf bound_ctrl:1
	v_pk_fma_f32 v[196:197], v[192:193], v[30:31], v[32:33] op_sel_hi:[1,0,1]
	v_add_f32_dpp v31, v180, v180 row_ror:8 row_mask:0xf bank_mask:0xf bound_ctrl:1
	v_cndmask_b32_e64 v199, v199, v31, s[30:31]
	v_pk_fma_f32 v[34:35], v[194:195], v[30:31], v[34:35] op_sel_hi:[1,0,1]
	ds_read_b128 v[30:33], v28 offset:23040
	ds_read_b128 v[180:183], v28 offset:23296
	ds_read_b128 v[184:187], v28 offset:23552
	ds_read_b128 v[188:191], v28 offset:24064
	ds_read_b128 v[192:195], v28 offset:24320
	ds_read_b32 v200, v29 offset:23808
	s_waitcnt lgkmcnt(8)
	v_pk_mul_f32 v[174:175], v[174:175], v[34:35]
	v_pk_mul_f32 v[162:163], v[162:163], v[34:35]
	v_pk_fma_f32 v[172:173], v[172:173], v[196:197], v[174:175]
	v_pk_fma_f32 v[160:161], v[160:161], v[196:197], v[162:163]
	v_add_f32_e32 v206, v172, v173
	v_pk_mul_f32 v[162:163], v[164:165], v[196:197]
	v_add_f32_e32 v160, v160, v161
	v_add_f32_dpp v161, v206, v206 quad_perm:[1,0,3,2] row_mask:0xf bank_mask:0xf bound_ctrl:1
	v_pk_mul_f32 v[34:35], v[166:167], v[34:35]
	v_add_f32_dpp v160, v160, v160 quad_perm:[1,0,3,2] row_mask:0xf bank_mask:0xf bound_ctrl:1
	s_waitcnt lgkmcnt(6)
	v_add_f32_dpp v161, v161, v161 quad_perm:[2,3,0,1] row_mask:0xf bank_mask:0xf bound_ctrl:1
	v_pk_fma_f32 v[34:35], v[170:171], v[198:199], v[34:35] op_sel_hi:[1,0,1]
	v_add_f32_dpp v160, v160, v160 quad_perm:[2,3,0,1] row_mask:0xf bank_mask:0xf bound_ctrl:1
	v_add_f32_dpp v161, v161, v161 row_ror:4 row_mask:0xf bank_mask:0xf bound_ctrl:1
	v_pk_fma_f32 v[162:163], v[168:169], v[198:199], v[162:163] op_sel_hi:[1,0,1]
	v_add_f32_dpp v164, v160, v160 row_ror:4 row_mask:0xf bank_mask:0xf bound_ctrl:1
	v_add_f32_dpp v160, v161, v161 row_ror:8 row_mask:0xf bank_mask:0xf bound_ctrl:1
	v_pk_fma_f32 v[196:197], v[176:177], v[160:161], v[162:163] op_sel_hi:[1,0,1]
	v_add_f32_dpp v161, v164, v164 row_ror:8 row_mask:0xf bank_mask:0xf bound_ctrl:1
	v_cndmask_b32_e64 v199, v199, v161, s[34:35]
	v_pk_fma_f32 v[34:35], v[178:179], v[160:161], v[34:35] op_sel_hi:[1,0,1]
	ds_read_b128 v[160:163], v28 offset:24576
	ds_read_b128 v[164:167], v28 offset:24832
	ds_read_b128 v[168:171], v28 offset:25088
	ds_read_b128 v[172:175], v28 offset:25600
	ds_read_b128 v[176:179], v28 offset:25856
	ds_read_b32 v198, v29 offset:25344
	s_waitcnt lgkmcnt(8)
	v_pk_mul_f32 v[190:191], v[190:191], v[34:35]
	v_pk_mul_f32 v[26:27], v[26:27], v[34:35]
	v_pk_fma_f32 v[188:189], v[188:189], v[196:197], v[190:191]
	v_pk_fma_f32 v[24:25], v[24:25], v[196:197], v[26:27]
	v_add_f32_e32 v206, v188, v189
	v_pk_mul_f32 v[26:27], v[180:181], v[196:197]
	v_add_f32_e32 v24, v24, v25
	v_add_f32_dpp v25, v206, v206 quad_perm:[1,0,3,2] row_mask:0xf bank_mask:0xf bound_ctrl:1
	v_pk_mul_f32 v[34:35], v[182:183], v[34:35]
	v_add_f32_dpp v24, v24, v24 quad_perm:[1,0,3,2] row_mask:0xf bank_mask:0xf bound_ctrl:1
	s_waitcnt lgkmcnt(6)
	v_add_f32_dpp v25, v25, v25 quad_perm:[2,3,0,1] row_mask:0xf bank_mask:0xf bound_ctrl:1
	v_pk_fma_f32 v[34:35], v[186:187], v[200:201], v[34:35] op_sel_hi:[1,0,1]
	v_add_f32_dpp v24, v24, v24 quad_perm:[2,3,0,1] row_mask:0xf bank_mask:0xf bound_ctrl:1
	v_add_f32_dpp v25, v25, v25 row_ror:4 row_mask:0xf bank_mask:0xf bound_ctrl:1
	v_pk_fma_f32 v[26:27], v[184:185], v[200:201], v[26:27] op_sel_hi:[1,0,1]
	v_add_f32_dpp v180, v24, v24 row_ror:4 row_mask:0xf bank_mask:0xf bound_ctrl:1
	v_add_f32_dpp v24, v25, v25 row_ror:8 row_mask:0xf bank_mask:0xf bound_ctrl:1
	v_pk_fma_f32 v[196:197], v[192:193], v[24:25], v[26:27] op_sel_hi:[1,0,1]
	v_add_f32_dpp v25, v180, v180 row_ror:8 row_mask:0xf bank_mask:0xf bound_ctrl:1
	v_cndmask_b32_e64 v199, v199, v25, s[36:37]
	v_pk_fma_f32 v[34:35], v[194:195], v[24:25], v[34:35] op_sel_hi:[1,0,1]
	ds_read_b128 v[24:27], v28 offset:26112
	ds_read_b128 v[180:183], v28 offset:26368
	ds_read_b128 v[184:187], v28 offset:26624
	ds_read_b128 v[188:191], v28 offset:27136
	ds_read_b128 v[192:195], v28 offset:27392
	ds_read_b32 v200, v29 offset:26880
	s_waitcnt lgkmcnt(8)
	v_pk_mul_f32 v[174:175], v[174:175], v[34:35]
	v_pk_mul_f32 v[32:33], v[32:33], v[34:35]
	v_pk_fma_f32 v[172:173], v[172:173], v[196:197], v[174:175]
	v_pk_fma_f32 v[30:31], v[30:31], v[196:197], v[32:33]
	v_add_f32_e32 v206, v172, v173
	v_pk_mul_f32 v[32:33], v[164:165], v[196:197]
	v_add_f32_e32 v30, v30, v31
	v_add_f32_dpp v31, v206, v206 quad_perm:[1,0,3,2] row_mask:0xf bank_mask:0xf bound_ctrl:1
	v_pk_mul_f32 v[34:35], v[166:167], v[34:35]
	v_add_f32_dpp v30, v30, v30 quad_perm:[1,0,3,2] row_mask:0xf bank_mask:0xf bound_ctrl:1
	s_waitcnt lgkmcnt(6)
	v_add_f32_dpp v31, v31, v31 quad_perm:[2,3,0,1] row_mask:0xf bank_mask:0xf bound_ctrl:1
	v_pk_fma_f32 v[34:35], v[170:171], v[198:199], v[34:35] op_sel_hi:[1,0,1]
	v_add_f32_dpp v30, v30, v30 quad_perm:[2,3,0,1] row_mask:0xf bank_mask:0xf bound_ctrl:1
	v_add_f32_dpp v31, v31, v31 row_ror:4 row_mask:0xf bank_mask:0xf bound_ctrl:1
	v_pk_fma_f32 v[32:33], v[168:169], v[198:199], v[32:33] op_sel_hi:[1,0,1]
	v_add_f32_dpp v30, v30, v30 row_ror:4 row_mask:0xf bank_mask:0xf bound_ctrl:1
	v_add_f32_dpp v164, v31, v31 row_ror:8 row_mask:0xf bank_mask:0xf bound_ctrl:1
	v_pk_fma_f32 v[196:197], v[176:177], v[164:165], v[32:33] op_sel_hi:[1,0,1]
	v_add_f32_dpp v30, v30, v30 row_ror:8 row_mask:0xf bank_mask:0xf bound_ctrl:1
	v_cndmask_b32_e64 v30, v199, v30, s[4:5]
	v_pk_fma_f32 v[198:199], v[178:179], v[164:165], v[34:35] op_sel_hi:[1,0,1]
	ds_read_b128 v[32:35], v28 offset:27648
	ds_read_b128 v[164:167], v28 offset:27904
	ds_read_b128 v[168:171], v28 offset:28160
	ds_read_b128 v[172:175], v28 offset:28672
	ds_read_b128 v[176:179], v28 offset:28928
	ds_read_b32 v202, v29 offset:28416
	s_waitcnt lgkmcnt(8)
; #define LAS __attribute__((address_space(3)))
; __device__ __forceinline__ void rwkv_scan_prompt(const Params& p, LAS unsigned char* lds, int bh, int rq) {
;     ...
;             for (int tk = 0; tk < TC; ++tk) {
;                 f32x4 nr4 = r4, nd4 = d4, nk4 = k4, na4 = a4, nb4 = b4; float nvv = vv;
;                 if (tk < TC - 1) {
;                     const LAS float* o = ob + (tk + 1) * 6 * 64;
;                     nr4 = *(const LAS f32x4*)(o + cg_ * 4); nd4 = *(const LAS f32x4*)(o + 64 + cg_ * 4); nk4 = *(const LAS f32x4*)(o + 128 + cg_ * 4);
;                     na4 = *(const LAS f32x4*)(o + 256 + cg_ * 4); nb4 = *(const LAS f32x4*)(o + 320 + cg_ * 4);
;                     nvv = o[192 + rq * 16 + rloc];
;                 }
;                 __builtin_amdgcn_sched_barrier(0);
;                 typedef float f32x2_ __attribute__((ext_vector_type(2)));
;                 f32x2_ ta = (f32x2_){S[0], S[1]} * (f32x2_){a4[0], a4[1]}; ta = (f32x2_){S[2], S[3]} * (f32x2_){a4[2], a4[3]} + ta;
;                 f32x2_ ty = (f32x2_){S[0], S[1]} * (f32x2_){rp[0], rp[1]}; ty = (f32x2_){S[2], S[3]} * (f32x2_){rp[2], rp[3]} + ty;
;                 const f32x4 T = S * d4 + vv * k4;
;                 float sa = ta[0] + ta[1];
;                 float yp = ty[0] + ty[1];
;                 sa = dpp_add<0xB1>(sa); yp = dpp_add<0xB1>(yp);
;                 sa = dpp_add<0x4E>(sa); yp = dpp_add<0x4E>(yp);
;                 sa = dpp_add<0x124>(sa); yp = dpp_add<0x124>(yp);
;                 sa = dpp_add<0x128>(sa); yp = dpp_add<0x128>(yp);
;                 if (tk > 0) yk[(tk - 1) >> 4] = (cg_ == ((tk - 1) & 15)) ? yp : yk[(tk - 1) >> 4];
;                 S = sa * b4 + T;
;                 rp = r4;
;                 r4 = nr4; d4 = nd4; k4 = nk4; a4 = na4; b4 = nb4; vv = nvv;
	v_pk_mul_f32 v[190:191], v[190:191], v[198:199]
	v_pk_mul_f32 v[162:163], v[162:163], v[198:199]
	v_pk_fma_f32 v[188:189], v[188:189], v[196:197], v[190:191]
	v_pk_fma_f32 v[160:161], v[160:161], v[196:197], v[162:163]
	v_add_f32_e32 v31, v188, v189
	v_add_f32_e32 v160, v160, v161
	v_pk_mul_f32 v[162:163], v[180:181], v[196:197]
	v_add_f32_dpp v31, v31, v31 quad_perm:[1,0,3,2] row_mask:0xf bank_mask:0xf bound_ctrl:1
	v_add_f32_dpp v160, v160, v160 quad_perm:[1,0,3,2] row_mask:0xf bank_mask:0xf bound_ctrl:1
	v_pk_mul_f32 v[180:181], v[182:183], v[198:199]
	v_add_f32_dpp v31, v31, v31 quad_perm:[2,3,0,1] row_mask:0xf bank_mask:0xf bound_ctrl:1
	v_add_f32_dpp v160, v160, v160 quad_perm:[2,3,0,1] row_mask:0xf bank_mask:0xf bound_ctrl:1
	s_waitcnt lgkmcnt(6)
	v_pk_fma_f32 v[180:181], v[186:187], v[200:201], v[180:181] op_sel_hi:[1,0,1]
	v_add_f32_dpp v31, v31, v31 row_ror:4 row_mask:0xf bank_mask:0xf bound_ctrl:1
	v_pk_fma_f32 v[162:163], v[184:185], v[200:201], v[162:163] op_sel_hi:[1,0,1]
	v_add_f32_dpp v161, v160, v160 row_ror:4 row_mask:0xf bank_mask:0xf bound_ctrl:1
	v_add_f32_dpp v160, v31, v31 row_ror:8 row_mask:0xf bank_mask:0xf bound_ctrl:1
	v_pk_fma_f32 v[196:197], v[192:193], v[160:161], v[162:163] op_sel_hi:[1,0,1]
	v_add_f32_dpp v31, v161, v161 row_ror:8 row_mask:0xf bank_mask:0xf bound_ctrl:1
	v_pk_fma_f32 v[198:199], v[194:195], v[160:161], v[180:181] op_sel_hi:[1,0,1]
	ds_read_b128 v[160:163], v28 offset:29184
	ds_read_b128 v[180:183], v28 offset:29440
	ds_read_b128 v[184:187], v28 offset:29696
	ds_read_b128 v[188:191], v28 offset:30208
	ds_read_b128 v[192:195], v28 offset:30464
	ds_read_b32 v200, v29 offset:29952
	v_cndmask_b32_e64 v31, 0, v31, s[6:7]
	s_waitcnt lgkmcnt(8)
	v_pk_mul_f32 v[174:175], v[174:175], v[198:199]
	v_pk_mul_f32 v[26:27], v[26:27], v[198:199]
	v_pk_fma_f32 v[172:173], v[172:173], v[196:197], v[174:175]
	v_pk_fma_f32 v[24:25], v[24:25], v[196:197], v[26:27]
	v_add_f32_e32 v206, v172, v173
	v_pk_mul_f32 v[26:27], v[164:165], v[196:197]
	v_add_f32_e32 v24, v24, v25
	s_waitcnt lgkmcnt(6)
	v_add_f32_dpp v25, v206, v206 quad_perm:[1,0,3,2] row_mask:0xf bank_mask:0xf bound_ctrl:1
	v_pk_mul_f32 v[164:165], v[166:167], v[198:199]
	v_add_f32_dpp v24, v24, v24 quad_perm:[1,0,3,2] row_mask:0xf bank_mask:0xf bound_ctrl:1
	v_add_f32_dpp v25, v25, v25 quad_perm:[2,3,0,1] row_mask:0xf bank_mask:0xf bound_ctrl:1
	v_pk_fma_f32 v[164:165], v[170:171], v[202:203], v[164:165] op_sel_hi:[1,0,1]
	v_add_f32_dpp v24, v24, v24 quad_perm:[2,3,0,1] row_mask:0xf bank_mask:0xf bound_ctrl:1
	v_add_f32_dpp v25, v25, v25 row_ror:4 row_mask:0xf bank_mask:0xf bound_ctrl:1
	v_pk_fma_f32 v[26:27], v[168:169], v[202:203], v[26:27] op_sel_hi:[1,0,1]
	v_add_f32_dpp v166, v24, v24 row_ror:4 row_mask:0xf bank_mask:0xf bound_ctrl:1
	v_add_f32_dpp v24, v25, v25 row_ror:8 row_mask:0xf bank_mask:0xf bound_ctrl:1
	v_pk_fma_f32 v[196:197], v[176:177], v[24:25], v[26:27] op_sel_hi:[1,0,1]
	v_add_f32_dpp v25, v166, v166 row_ror:8 row_mask:0xf bank_mask:0xf bound_ctrl:1
	v_cndmask_b32_e64 v31, v31, v25, s[8:9]
	v_pk_fma_f32 v[198:199], v[178:179], v[24:25], v[164:165] op_sel_hi:[1,0,1]
	ds_read_b128 v[24:27], v28 offset:30720
	ds_read_b128 v[164:167], v28 offset:30976
	ds_read_b128 v[168:171], v28 offset:31232
	ds_read_b128 v[172:175], v28 offset:31744
	ds_read_b128 v[176:179], v28 offset:32000
	ds_read_b32 v202, v29 offset:31488
	s_waitcnt lgkmcnt(8)
	v_pk_mul_f32 v[190:191], v[190:191], v[198:199]
	v_pk_mul_f32 v[34:35], v[34:35], v[198:199]
	v_pk_fma_f32 v[188:189], v[188:189], v[196:197], v[190:191]
	v_pk_fma_f32 v[32:33], v[32:33], v[196:197], v[34:35]
	v_add_f32_e32 v206, v188, v189
	v_pk_mul_f32 v[34:35], v[180:181], v[196:197]
	v_add_f32_e32 v32, v32, v33
	s_waitcnt lgkmcnt(6)
	v_add_f32_dpp v33, v206, v206 quad_perm:[1,0,3,2] row_mask:0xf bank_mask:0xf bound_ctrl:1
	v_pk_mul_f32 v[180:181], v[182:183], v[198:199]
	v_add_f32_dpp v32, v32, v32 quad_perm:[1,0,3,2] row_mask:0xf bank_mask:0xf bound_ctrl:1
	v_add_f32_dpp v33, v33, v33 quad_perm:[2,3,0,1] row_mask:0xf bank_mask:0xf bound_ctrl:1
	v_pk_fma_f32 v[180:181], v[186:187], v[200:201], v[180:181] op_sel_hi:[1,0,1]
	v_add_f32_dpp v32, v32, v32 quad_perm:[2,3,0,1] row_mask:0xf bank_mask:0xf bound_ctrl:1
	v_add_f32_dpp v33, v33, v33 row_ror:4 row_mask:0xf bank_mask:0xf bound_ctrl:1
	v_pk_fma_f32 v[34:35], v[184:185], v[200:201], v[34:35] op_sel_hi:[1,0,1]
	v_add_f32_dpp v182, v32, v32 row_ror:4 row_mask:0xf bank_mask:0xf bound_ctrl:1
	v_add_f32_dpp v32, v33, v33 row_ror:8 row_mask:0xf bank_mask:0xf bound_ctrl:1
	v_pk_fma_f32 v[196:197], v[192:193], v[32:33], v[34:35] op_sel_hi:[1,0,1]
	v_add_f32_dpp v33, v182, v182 row_ror:8 row_mask:0xf bank_mask:0xf bound_ctrl:1
	v_cndmask_b32_e64 v31, v31, v33, s[10:11]
	v_pk_fma_f32 v[198:199], v[194:195], v[32:33], v[180:181] op_sel_hi:[1,0,1]
	ds_read_b128 v[32:35], v28 offset:32256
	ds_read_b128 v[180:183], v28 offset:32512
	ds_read_b128 v[184:187], v28 offset:32768
	ds_read_b128 v[188:191], v28 offset:33280
	ds_read_b128 v[192:195], v28 offset:33536
	ds_read_b32 v200, v29 offset:33024
	s_waitcnt lgkmcnt(8)
	v_pk_mul_f32 v[174:175], v[174:175], v[198:199]
	v_pk_mul_f32 v[162:163], v[162:163], v[198:199]
	v_pk_fma_f32 v[172:173], v[172:173], v[196:197], v[174:175]
	v_pk_fma_f32 v[160:161], v[160:161], v[196:197], v[162:163]
	v_add_f32_e32 v206, v172, v173
	v_pk_mul_f32 v[162:163], v[164:165], v[196:197]
	v_add_f32_e32 v160, v160, v161
	s_waitcnt lgkmcnt(6)
; #define LAS __attribute__((address_space(3)))
; __device__ __forceinline__ void rwkv_scan_prompt(const Params& p, LAS unsigned char* lds, int bh, int rq) {
;     ...
;             for (int tk = 0; tk < TC; ++tk) {
;                 f32x4 nr4 = r4, nd4 = d4, nk4 = k4, na4 = a4, nb4 = b4; float nvv = vv;
;                 if (tk < TC - 1) {
;                     const LAS float* o = ob + (tk + 1) * 6 * 64;
;                     nr4 = *(const LAS f32x4*)(o + cg_ * 4); nd4 = *(const LAS f32x4*)(o + 64 + cg_ * 4); nk4 = *(const LAS f32x4*)(o + 128 + cg_ * 4);
;                     na4 = *(const LAS f32x4*)(o + 256 + cg_ * 4); nb4 = *(const LAS f32x4*)(o + 320 + cg_ * 4);
;                     nvv = o[192 + rq * 16 + rloc];
;                 }
;                 __builtin_amdgcn_sched_barrier(0);
;                 typedef float f32x2_ __attribute__((ext_vector_type(2)));
;                 f32x2_ ta = (f32x2_){S[0], S[1]} * (f32x2_){a4[0], a4[1]}; ta = (f32x2_){S[2], S[3]} * (f32x2_){a4[2], a4[3]} + ta;
;                 f32x2_ ty = (f32x2_){S[0], S[1]} * (f32x2_){rp[0], rp[1]}; ty = (f32x2_){S[2], S[3]} * (f32x2_){rp[2], rp[3]} + ty;
;                 const f32x4 T = S * d4 + vv * k4;
;                 float sa = ta[0] + ta[1];
;                 float yp = ty[0] + ty[1];
;                 sa = dpp_add<0xB1>(sa); yp = dpp_add<0xB1>(yp);
;                 sa = dpp_add<0x4E>(sa); yp = dpp_add<0x4E>(yp);
;                 sa = dpp_add<0x124>(sa); yp = dpp_add<0x124>(yp);
;                 sa = dpp_add<0x128>(sa); yp = dpp_add<0x128>(yp);
;                 if (tk > 0) yk[(tk - 1) >> 4] = (cg_ == ((tk - 1) & 15)) ? yp : yk[(tk - 1) >> 4];
;                 S = sa * b4 + T;
;                 rp = r4;
;                 r4 = nr4; d4 = nd4; k4 = nk4; a4 = na4; b4 = nb4; vv = nvv;
	v_add_f32_dpp v161, v206, v206 quad_perm:[1,0,3,2] row_mask:0xf bank_mask:0xf bound_ctrl:1
	v_pk_mul_f32 v[164:165], v[166:167], v[198:199]
	v_add_f32_dpp v160, v160, v160 quad_perm:[1,0,3,2] row_mask:0xf bank_mask:0xf bound_ctrl:1
	v_add_f32_dpp v161, v161, v161 quad_perm:[2,3,0,1] row_mask:0xf bank_mask:0xf bound_ctrl:1
	v_pk_fma_f32 v[164:165], v[170:171], v[202:203], v[164:165] op_sel_hi:[1,0,1]
	v_add_f32_dpp v160, v160, v160 quad_perm:[2,3,0,1] row_mask:0xf bank_mask:0xf bound_ctrl:1
	v_add_f32_dpp v161, v161, v161 row_ror:4 row_mask:0xf bank_mask:0xf bound_ctrl:1
	v_pk_fma_f32 v[162:163], v[168:169], v[202:203], v[162:163] op_sel_hi:[1,0,1]
	v_add_f32_dpp v166, v160, v160 row_ror:4 row_mask:0xf bank_mask:0xf bound_ctrl:1
	v_add_f32_dpp v160, v161, v161 row_ror:8 row_mask:0xf bank_mask:0xf bound_ctrl:1
	v_pk_fma_f32 v[196:197], v[176:177], v[160:161], v[162:163] op_sel_hi:[1,0,1]
	v_add_f32_dpp v161, v166, v166 row_ror:8 row_mask:0xf bank_mask:0xf bound_ctrl:1
	v_cndmask_b32_e64 v31, v31, v161, s[12:13]
	v_pk_fma_f32 v[198:199], v[178:179], v[160:161], v[164:165] op_sel_hi:[1,0,1]
	ds_read_b128 v[160:163], v28 offset:33792
	ds_read_b128 v[164:167], v28 offset:34048
	ds_read_b128 v[168:171], v28 offset:34304
	ds_read_b128 v[172:175], v28 offset:34816
	ds_read_b128 v[176:179], v28 offset:35072
	ds_read_b32 v202, v29 offset:34560
	s_waitcnt lgkmcnt(8)
	v_pk_mul_f32 v[190:191], v[190:191], v[198:199]
	v_pk_mul_f32 v[26:27], v[26:27], v[198:199]
	v_pk_fma_f32 v[188:189], v[188:189], v[196:197], v[190:191]
	v_pk_fma_f32 v[24:25], v[24:25], v[196:197], v[26:27]
	v_add_f32_e32 v206, v188, v189
	v_pk_mul_f32 v[26:27], v[180:181], v[196:197]
	v_add_f32_e32 v24, v24, v25
	s_waitcnt lgkmcnt(6)
	v_add_f32_dpp v25, v206, v206 quad_perm:[1,0,3,2] row_mask:0xf bank_mask:0xf bound_ctrl:1
	v_pk_mul_f32 v[180:181], v[182:183], v[198:199]
	v_add_f32_dpp v24, v24, v24 quad_perm:[1,0,3,2] row_mask:0xf bank_mask:0xf bound_ctrl:1
	v_add_f32_dpp v25, v25, v25 quad_perm:[2,3,0,1] row_mask:0xf bank_mask:0xf bound_ctrl:1
	v_pk_fma_f32 v[180:181], v[186:187], v[200:201], v[180:181] op_sel_hi:[1,0,1]
	v_add_f32_dpp v24, v24, v24 quad_perm:[2,3,0,1] row_mask:0xf bank_mask:0xf bound_ctrl:1
	v_add_f32_dpp v25, v25, v25 row_ror:4 row_mask:0xf bank_mask:0xf bound_ctrl:1
	v_pk_fma_f32 v[26:27], v[184:185], v[200:201], v[26:27] op_sel_hi:[1,0,1]
	v_add_f32_dpp v182, v24, v24 row_ror:4 row_mask:0xf bank_mask:0xf bound_ctrl:1
	v_add_f32_dpp v24, v25, v25 row_ror:8 row_mask:0xf bank_mask:0xf bound_ctrl:1
	v_pk_fma_f32 v[196:197], v[192:193], v[24:25], v[26:27] op_sel_hi:[1,0,1]
	v_add_f32_dpp v25, v182, v182 row_ror:8 row_mask:0xf bank_mask:0xf bound_ctrl:1
	v_cndmask_b32_e64 v31, v31, v25, s[14:15]
	v_pk_fma_f32 v[198:199], v[194:195], v[24:25], v[180:181] op_sel_hi:[1,0,1]
	ds_read_b128 v[24:27], v28 offset:35328
	ds_read_b128 v[180:183], v28 offset:35584
	ds_read_b128 v[184:187], v28 offset:35840
	ds_read_b128 v[188:191], v28 offset:36352
	ds_read_b128 v[192:195], v28 offset:36608
	ds_read_b32 v200, v29 offset:36096
	s_waitcnt lgkmcnt(8)
	v_pk_mul_f32 v[174:175], v[174:175], v[198:199]
	v_pk_mul_f32 v[34:35], v[34:35], v[198:199]
	v_pk_fma_f32 v[172:173], v[172:173], v[196:197], v[174:175]
	v_pk_fma_f32 v[32:33], v[32:33], v[196:197], v[34:35]
	v_add_f32_e32 v206, v172, v173
	v_pk_mul_f32 v[34:35], v[164:165], v[196:197]
	v_add_f32_e32 v32, v32, v33
	s_waitcnt lgkmcnt(6)
	v_add_f32_dpp v33, v206, v206 quad_perm:[1,0,3,2] row_mask:0xf bank_mask:0xf bound_ctrl:1
	v_pk_mul_f32 v[164:165], v[166:167], v[198:199]
	v_add_f32_dpp v32, v32, v32 quad_perm:[1,0,3,2] row_mask:0xf bank_mask:0xf bound_ctrl:1
	v_add_f32_dpp v33, v33, v33 quad_perm:[2,3,0,1] row_mask:0xf bank_mask:0xf bound_ctrl:1
	v_pk_fma_f32 v[164:165], v[170:171], v[202:203], v[164:165] op_sel_hi:[1,0,1]
	v_add_f32_dpp v32, v32, v32 quad_perm:[2,3,0,1] row_mask:0xf bank_mask:0xf bound_ctrl:1
	v_add_f32_dpp v33, v33, v33 row_ror:4 row_mask:0xf bank_mask:0xf bound_ctrl:1
	v_pk_fma_f32 v[34:35], v[168:169], v[202:203], v[34:35] op_sel_hi:[1,0,1]
	v_add_f32_dpp v166, v32, v32 row_ror:4 row_mask:0xf bank_mask:0xf bound_ctrl:1
	v_add_f32_dpp v32, v33, v33 row_ror:8 row_mask:0xf bank_mask:0xf bound_ctrl:1
	v_pk_fma_f32 v[196:197], v[176:177], v[32:33], v[34:35] op_sel_hi:[1,0,1]
	v_add_f32_dpp v33, v166, v166 row_ror:8 row_mask:0xf bank_mask:0xf bound_ctrl:1
	v_cndmask_b32_e64 v31, v31, v33, s[16:17]
	v_pk_fma_f32 v[198:199], v[178:179], v[32:33], v[164:165] op_sel_hi:[1,0,1]
	ds_read_b128 v[32:35], v28 offset:36864
	ds_read_b128 v[164:167], v28 offset:37120
	ds_read_b128 v[168:171], v28 offset:37376
	ds_read_b128 v[172:175], v28 offset:37888
	ds_read_b128 v[176:179], v28 offset:38144
	ds_read_b32 v202, v29 offset:37632
	s_waitcnt lgkmcnt(8)
	v_pk_mul_f32 v[190:191], v[190:191], v[198:199]
	v_pk_mul_f32 v[162:163], v[162:163], v[198:199]
	v_pk_fma_f32 v[188:189], v[188:189], v[196:197], v[190:191]
	v_pk_fma_f32 v[160:161], v[160:161], v[196:197], v[162:163]
	v_add_f32_e32 v206, v188, v189
	v_pk_mul_f32 v[162:163], v[180:181], v[196:197]
	v_add_f32_e32 v160, v160, v161
	s_waitcnt lgkmcnt(6)
; #define LAS __attribute__((address_space(3)))
; __device__ __forceinline__ void rwkv_scan_prompt(const Params& p, LAS unsigned char* lds, int bh, int rq) {
;     ...
;             for (int tk = 0; tk < TC; ++tk) {
;                 f32x4 nr4 = r4, nd4 = d4, nk4 = k4, na4 = a4, nb4 = b4; float nvv = vv;
;                 if (tk < TC - 1) {
;                     const LAS float* o = ob + (tk + 1) * 6 * 64;
;                     nr4 = *(const LAS f32x4*)(o + cg_ * 4); nd4 = *(const LAS f32x4*)(o + 64 + cg_ * 4); nk4 = *(const LAS f32x4*)(o + 128 + cg_ * 4);
;                     na4 = *(const LAS f32x4*)(o + 256 + cg_ * 4); nb4 = *(const LAS f32x4*)(o + 320 + cg_ * 4);
;                     nvv = o[192 + rq * 16 + rloc];
;                 }
;                 __builtin_amdgcn_sched_barrier(0);
;                 typedef float f32x2_ __attribute__((ext_vector_type(2)));
;                 f32x2_ ta = (f32x2_){S[0], S[1]} * (f32x2_){a4[0], a4[1]}; ta = (f32x2_){S[2], S[3]} * (f32x2_){a4[2], a4[3]} + ta;
;                 f32x2_ ty = (f32x2_){S[0], S[1]} * (f32x2_){rp[0], rp[1]}; ty = (f32x2_){S[2], S[3]} * (f32x2_){rp[2], rp[3]} + ty;
;                 const f32x4 T = S * d4 + vv * k4;
;                 float sa = ta[0] + ta[1];
;                 float yp = ty[0] + ty[1];
;                 sa = dpp_add<0xB1>(sa); yp = dpp_add<0xB1>(yp);
;                 sa = dpp_add<0x4E>(sa); yp = dpp_add<0x4E>(yp);
;                 sa = dpp_add<0x124>(sa); yp = dpp_add<0x124>(yp);
;                 sa = dpp_add<0x128>(sa); yp = dpp_add<0x128>(yp);
;                 if (tk > 0) yk[(tk - 1) >> 4] = (cg_ == ((tk - 1) & 15)) ? yp : yk[(tk - 1) >> 4];
;                 S = sa * b4 + T;
;                 rp = r4;
;                 r4 = nr4; d4 = nd4; k4 = nk4; a4 = na4; b4 = nb4; vv = nvv;
	v_add_f32_dpp v161, v206, v206 quad_perm:[1,0,3,2] row_mask:0xf bank_mask:0xf bound_ctrl:1
	v_pk_mul_f32 v[180:181], v[182:183], v[198:199]
	v_add_f32_dpp v160, v160, v160 quad_perm:[1,0,3,2] row_mask:0xf bank_mask:0xf bound_ctrl:1
	v_add_f32_dpp v161, v161, v161 quad_perm:[2,3,0,1] row_mask:0xf bank_mask:0xf bound_ctrl:1
	v_pk_fma_f32 v[180:181], v[186:187], v[200:201], v[180:181] op_sel_hi:[1,0,1]
	v_add_f32_dpp v160, v160, v160 quad_perm:[2,3,0,1] row_mask:0xf bank_mask:0xf bound_ctrl:1
	v_add_f32_dpp v161, v161, v161 row_ror:4 row_mask:0xf bank_mask:0xf bound_ctrl:1
	v_pk_fma_f32 v[162:163], v[184:185], v[200:201], v[162:163] op_sel_hi:[1,0,1]
	v_add_f32_dpp v182, v160, v160 row_ror:4 row_mask:0xf bank_mask:0xf bound_ctrl:1
	v_add_f32_dpp v160, v161, v161 row_ror:8 row_mask:0xf bank_mask:0xf bound_ctrl:1
	v_pk_fma_f32 v[196:197], v[192:193], v[160:161], v[162:163] op_sel_hi:[1,0,1]
	v_add_f32_dpp v161, v182, v182 row_ror:8 row_mask:0xf bank_mask:0xf bound_ctrl:1
	v_cndmask_b32_e64 v31, v31, v161, s[18:19]
	v_pk_fma_f32 v[198:199], v[194:195], v[160:161], v[180:181] op_sel_hi:[1,0,1]
	ds_read_b128 v[160:163], v28 offset:38400
	ds_read_b128 v[180:183], v28 offset:38656
	ds_read_b128 v[184:187], v28 offset:38912
	ds_read_b128 v[188:191], v28 offset:39424
	ds_read_b128 v[192:195], v28 offset:39680
	ds_read_b32 v200, v29 offset:39168
	s_waitcnt lgkmcnt(8)
	v_pk_mul_f32 v[174:175], v[174:175], v[198:199]
	v_pk_mul_f32 v[26:27], v[26:27], v[198:199]
	v_pk_fma_f32 v[172:173], v[172:173], v[196:197], v[174:175]
	v_pk_fma_f32 v[24:25], v[24:25], v[196:197], v[26:27]
	v_add_f32_e32 v206, v172, v173
	v_pk_mul_f32 v[26:27], v[164:165], v[196:197]
	v_add_f32_e32 v24, v24, v25
	s_waitcnt lgkmcnt(6)
	v_add_f32_dpp v25, v206, v206 quad_perm:[1,0,3,2] row_mask:0xf bank_mask:0xf bound_ctrl:1
	v_pk_mul_f32 v[164:165], v[166:167], v[198:199]
	v_add_f32_dpp v24, v24, v24 quad_perm:[1,0,3,2] row_mask:0xf bank_mask:0xf bound_ctrl:1
	v_add_f32_dpp v25, v25, v25 quad_perm:[2,3,0,1] row_mask:0xf bank_mask:0xf bound_ctrl:1
	v_pk_fma_f32 v[164:165], v[170:171], v[202:203], v[164:165] op_sel_hi:[1,0,1]
	v_add_f32_dpp v24, v24, v24 quad_perm:[2,3,0,1] row_mask:0xf bank_mask:0xf bound_ctrl:1
	v_add_f32_dpp v25, v25, v25 row_ror:4 row_mask:0xf bank_mask:0xf bound_ctrl:1
	v_pk_fma_f32 v[26:27], v[168:169], v[202:203], v[26:27] op_sel_hi:[1,0,1]
	v_add_f32_dpp v166, v24, v24 row_ror:4 row_mask:0xf bank_mask:0xf bound_ctrl:1
	v_add_f32_dpp v24, v25, v25 row_ror:8 row_mask:0xf bank_mask:0xf bound_ctrl:1
	v_pk_fma_f32 v[196:197], v[176:177], v[24:25], v[26:27] op_sel_hi:[1,0,1]
	v_add_f32_dpp v25, v166, v166 row_ror:8 row_mask:0xf bank_mask:0xf bound_ctrl:1
	v_cndmask_b32_e64 v31, v31, v25, s[20:21]
	v_pk_fma_f32 v[198:199], v[178:179], v[24:25], v[164:165] op_sel_hi:[1,0,1]
	ds_read_b128 v[24:27], v28 offset:39936
	ds_read_b128 v[164:167], v28 offset:40192
	ds_read_b128 v[168:171], v28 offset:40448
	ds_read_b128 v[172:175], v28 offset:40960
	ds_read_b128 v[176:179], v28 offset:41216
	ds_read_b32 v202, v29 offset:40704
	s_waitcnt lgkmcnt(8)
	v_pk_mul_f32 v[190:191], v[190:191], v[198:199]
	v_pk_mul_f32 v[34:35], v[34:35], v[198:199]
	v_pk_fma_f32 v[188:189], v[188:189], v[196:197], v[190:191]
	v_pk_fma_f32 v[32:33], v[32:33], v[196:197], v[34:35]
	v_add_f32_e32 v206, v188, v189
	v_pk_mul_f32 v[34:35], v[180:181], v[196:197]
	v_add_f32_e32 v32, v32, v33
	s_waitcnt lgkmcnt(6)
	v_add_f32_dpp v33, v206, v206 quad_perm:[1,0,3,2] row_mask:0xf bank_mask:0xf bound_ctrl:1
	v_pk_mul_f32 v[180:181], v[182:183], v[198:199]
	v_add_f32_dpp v32, v32, v32 quad_perm:[1,0,3,2] row_mask:0xf bank_mask:0xf bound_ctrl:1
	v_add_f32_dpp v33, v33, v33 quad_perm:[2,3,0,1] row_mask:0xf bank_mask:0xf bound_ctrl:1
	v_pk_fma_f32 v[180:181], v[186:187], v[200:201], v[180:181] op_sel_hi:[1,0,1]
	v_add_f32_dpp v32, v32, v32 quad_perm:[2,3,0,1] row_mask:0xf bank_mask:0xf bound_ctrl:1
	v_add_f32_dpp v33, v33, v33 row_ror:4 row_mask:0xf bank_mask:0xf bound_ctrl:1
	v_pk_fma_f32 v[34:35], v[184:185], v[200:201], v[34:35] op_sel_hi:[1,0,1]
	v_add_f32_dpp v182, v32, v32 row_ror:4 row_mask:0xf bank_mask:0xf bound_ctrl:1
	v_add_f32_dpp v32, v33, v33 row_ror:8 row_mask:0xf bank_mask:0xf bound_ctrl:1
	v_pk_fma_f32 v[196:197], v[192:193], v[32:33], v[34:35] op_sel_hi:[1,0,1]
	v_add_f32_dpp v33, v182, v182 row_ror:8 row_mask:0xf bank_mask:0xf bound_ctrl:1
	v_cndmask_b32_e64 v31, v31, v33, s[22:23]
	v_pk_fma_f32 v[198:199], v[194:195], v[32:33], v[180:181] op_sel_hi:[1,0,1]
	ds_read_b128 v[32:35], v28 offset:41472
	ds_read_b128 v[180:183], v28 offset:41728
	ds_read_b128 v[184:187], v28 offset:41984
	ds_read_b128 v[188:191], v28 offset:42496
	ds_read_b128 v[192:195], v28 offset:42752
	ds_read_b32 v200, v29 offset:42240
	s_waitcnt lgkmcnt(8)
	v_pk_mul_f32 v[174:175], v[174:175], v[198:199]
	v_pk_mul_f32 v[162:163], v[162:163], v[198:199]
	v_pk_fma_f32 v[172:173], v[172:173], v[196:197], v[174:175]
	v_pk_fma_f32 v[160:161], v[160:161], v[196:197], v[162:163]
	v_add_f32_e32 v206, v172, v173
	v_pk_mul_f32 v[162:163], v[164:165], v[196:197]
	v_add_f32_e32 v160, v160, v161
	s_waitcnt lgkmcnt(6)
; #define LAS __attribute__((address_space(3)))
; __device__ __forceinline__ void rwkv_scan_prompt(const Params& p, LAS unsigned char* lds, int bh, int rq) {
;     ...
;             for (int tk = 0; tk < TC; ++tk) {
;                 f32x4 nr4 = r4, nd4 = d4, nk4 = k4, na4 = a4, nb4 = b4; float nvv = vv;
;                 if (tk < TC - 1) {
;                     const LAS float* o = ob + (tk + 1) * 6 * 64;
;                     nr4 = *(const LAS f32x4*)(o + cg_ * 4); nd4 = *(const LAS f32x4*)(o + 64 + cg_ * 4); nk4 = *(const LAS f32x4*)(o + 128 + cg_ * 4);
;                     na4 = *(const LAS f32x4*)(o + 256 + cg_ * 4); nb4 = *(const LAS f32x4*)(o + 320 + cg_ * 4);
;                     nvv = o[192 + rq * 16 + rloc];
;                 }
;                 __builtin_amdgcn_sched_barrier(0);
;                 typedef float f32x2_ __attribute__((ext_vector_type(2)));
;                 f32x2_ ta = (f32x2_){S[0], S[1]} * (f32x2_){a4[0], a4[1]}; ta = (f32x2_){S[2], S[3]} * (f32x2_){a4[2], a4[3]} + ta;
;                 f32x2_ ty = (f32x2_){S[0], S[1]} * (f32x2_){rp[0], rp[1]}; ty = (f32x2_){S[2], S[3]} * (f32x2_){rp[2], rp[3]} + ty;
;                 const f32x4 T = S * d4 + vv * k4;
;                 float sa = ta[0] + ta[1];
;                 float yp = ty[0] + ty[1];
;                 sa = dpp_add<0xB1>(sa); yp = dpp_add<0xB1>(yp);
;                 sa = dpp_add<0x4E>(sa); yp = dpp_add<0x4E>(yp);
;                 sa = dpp_add<0x124>(sa); yp = dpp_add<0x124>(yp);
;                 sa = dpp_add<0x128>(sa); yp = dpp_add<0x128>(yp);
;                 if (tk > 0) yk[(tk - 1) >> 4] = (cg_ == ((tk - 1) & 15)) ? yp : yk[(tk - 1) >> 4];
;                 S = sa * b4 + T;
;                 rp = r4;
;                 r4 = nr4; d4 = nd4; k4 = nk4; a4 = na4; b4 = nb4; vv = nvv;
	v_add_f32_dpp v161, v206, v206 quad_perm:[1,0,3,2] row_mask:0xf bank_mask:0xf bound_ctrl:1
	v_pk_mul_f32 v[164:165], v[166:167], v[198:199]
	v_add_f32_dpp v160, v160, v160 quad_perm:[1,0,3,2] row_mask:0xf bank_mask:0xf bound_ctrl:1
	v_add_f32_dpp v161, v161, v161 quad_perm:[2,3,0,1] row_mask:0xf bank_mask:0xf bound_ctrl:1
	v_pk_fma_f32 v[164:165], v[170:171], v[202:203], v[164:165] op_sel_hi:[1,0,1]
	v_add_f32_dpp v160, v160, v160 quad_perm:[2,3,0,1] row_mask:0xf bank_mask:0xf bound_ctrl:1
	v_add_f32_dpp v161, v161, v161 row_ror:4 row_mask:0xf bank_mask:0xf bound_ctrl:1
	v_pk_fma_f32 v[162:163], v[168:169], v[202:203], v[162:163] op_sel_hi:[1,0,1]
	v_add_f32_dpp v166, v160, v160 row_ror:4 row_mask:0xf bank_mask:0xf bound_ctrl:1
	v_add_f32_dpp v160, v161, v161 row_ror:8 row_mask:0xf bank_mask:0xf bound_ctrl:1
	v_pk_fma_f32 v[196:197], v[176:177], v[160:161], v[162:163] op_sel_hi:[1,0,1]
	v_add_f32_dpp v161, v166, v166 row_ror:8 row_mask:0xf bank_mask:0xf bound_ctrl:1
	v_cndmask_b32_e64 v31, v31, v161, s[24:25]
	v_pk_fma_f32 v[198:199], v[178:179], v[160:161], v[164:165] op_sel_hi:[1,0,1]
	ds_read_b128 v[160:163], v28 offset:43008
	ds_read_b128 v[164:167], v28 offset:43264
	ds_read_b128 v[168:171], v28 offset:43520
	ds_read_b128 v[172:175], v28 offset:44032
	ds_read_b128 v[176:179], v28 offset:44288
	ds_read_b32 v202, v29 offset:43776
	s_waitcnt lgkmcnt(8)
	v_pk_mul_f32 v[190:191], v[190:191], v[198:199]
	v_pk_mul_f32 v[26:27], v[26:27], v[198:199]
	v_pk_fma_f32 v[188:189], v[188:189], v[196:197], v[190:191]
	v_pk_fma_f32 v[24:25], v[24:25], v[196:197], v[26:27]
	v_add_f32_e32 v206, v188, v189
	v_pk_mul_f32 v[26:27], v[180:181], v[196:197]
	v_add_f32_e32 v24, v24, v25
	s_waitcnt lgkmcnt(6)
	v_add_f32_dpp v25, v206, v206 quad_perm:[1,0,3,2] row_mask:0xf bank_mask:0xf bound_ctrl:1
	v_pk_mul_f32 v[180:181], v[182:183], v[198:199]
	v_add_f32_dpp v24, v24, v24 quad_perm:[1,0,3,2] row_mask:0xf bank_mask:0xf bound_ctrl:1
	v_add_f32_dpp v25, v25, v25 quad_perm:[2,3,0,1] row_mask:0xf bank_mask:0xf bound_ctrl:1
	v_pk_fma_f32 v[180:181], v[186:187], v[200:201], v[180:181] op_sel_hi:[1,0,1]
	v_add_f32_dpp v24, v24, v24 quad_perm:[2,3,0,1] row_mask:0xf bank_mask:0xf bound_ctrl:1
	v_add_f32_dpp v25, v25, v25 row_ror:4 row_mask:0xf bank_mask:0xf bound_ctrl:1
	v_pk_fma_f32 v[26:27], v[184:185], v[200:201], v[26:27] op_sel_hi:[1,0,1]
	v_add_f32_dpp v182, v24, v24 row_ror:4 row_mask:0xf bank_mask:0xf bound_ctrl:1
	v_add_f32_dpp v24, v25, v25 row_ror:8 row_mask:0xf bank_mask:0xf bound_ctrl:1
	v_pk_fma_f32 v[196:197], v[192:193], v[24:25], v[26:27] op_sel_hi:[1,0,1]
	v_add_f32_dpp v25, v182, v182 row_ror:8 row_mask:0xf bank_mask:0xf bound_ctrl:1
	v_cndmask_b32_e64 v31, v31, v25, s[26:27]
	v_pk_fma_f32 v[198:199], v[194:195], v[24:25], v[180:181] op_sel_hi:[1,0,1]
	ds_read_b128 v[24:27], v28 offset:44544
	ds_read_b128 v[180:183], v28 offset:44800
	ds_read_b128 v[184:187], v28 offset:45056
	ds_read_b128 v[188:191], v28 offset:45568
	ds_read_b128 v[192:195], v28 offset:45824
	ds_read_b32 v200, v29 offset:45312
	s_waitcnt lgkmcnt(8)
	v_pk_mul_f32 v[174:175], v[174:175], v[198:199]
	v_pk_mul_f32 v[34:35], v[34:35], v[198:199]
	v_pk_fma_f32 v[172:173], v[172:173], v[196:197], v[174:175]
	v_pk_fma_f32 v[32:33], v[32:33], v[196:197], v[34:35]
	v_add_f32_e32 v206, v172, v173
	v_pk_mul_f32 v[34:35], v[164:165], v[196:197]
	v_add_f32_e32 v32, v32, v33
	s_waitcnt lgkmcnt(6)
	v_add_f32_dpp v33, v206, v206 quad_perm:[1,0,3,2] row_mask:0xf bank_mask:0xf bound_ctrl:1
	v_pk_mul_f32 v[164:165], v[166:167], v[198:199]
	v_add_f32_dpp v32, v32, v32 quad_perm:[1,0,3,2] row_mask:0xf bank_mask:0xf bound_ctrl:1
	v_add_f32_dpp v33, v33, v33 quad_perm:[2,3,0,1] row_mask:0xf bank_mask:0xf bound_ctrl:1
	v_pk_fma_f32 v[164:165], v[170:171], v[202:203], v[164:165] op_sel_hi:[1,0,1]
	v_add_f32_dpp v32, v32, v32 quad_perm:[2,3,0,1] row_mask:0xf bank_mask:0xf bound_ctrl:1
	v_add_f32_dpp v33, v33, v33 row_ror:4 row_mask:0xf bank_mask:0xf bound_ctrl:1
	v_pk_fma_f32 v[34:35], v[168:169], v[202:203], v[34:35] op_sel_hi:[1,0,1]
	v_add_f32_dpp v166, v32, v32 row_ror:4 row_mask:0xf bank_mask:0xf bound_ctrl:1
	v_add_f32_dpp v32, v33, v33 row_ror:8 row_mask:0xf bank_mask:0xf bound_ctrl:1
	v_pk_fma_f32 v[196:197], v[176:177], v[32:33], v[34:35] op_sel_hi:[1,0,1]
	v_add_f32_dpp v33, v166, v166 row_ror:8 row_mask:0xf bank_mask:0xf bound_ctrl:1
	v_cndmask_b32_e64 v31, v31, v33, s[28:29]
	v_pk_fma_f32 v[198:199], v[178:179], v[32:33], v[164:165] op_sel_hi:[1,0,1]
	ds_read_b128 v[32:35], v28 offset:46080
	ds_read_b128 v[164:167], v28 offset:46336
	ds_read_b128 v[168:171], v28 offset:46592
	ds_read_b128 v[172:175], v28 offset:47104
	ds_read_b128 v[176:179], v28 offset:47360
	ds_read_b32 v202, v29 offset:46848
	s_waitcnt lgkmcnt(8)
	v_pk_mul_f32 v[190:191], v[190:191], v[198:199]
	v_pk_mul_f32 v[162:163], v[162:163], v[198:199]
	v_pk_fma_f32 v[188:189], v[188:189], v[196:197], v[190:191]
	v_pk_fma_f32 v[160:161], v[160:161], v[196:197], v[162:163]
	v_add_f32_e32 v206, v188, v189
	v_pk_mul_f32 v[162:163], v[180:181], v[196:197]
	v_add_f32_e32 v160, v160, v161
	s_waitcnt lgkmcnt(6)
; #define LAS __attribute__((address_space(3)))
; __device__ __forceinline__ void rwkv_scan_prompt(const Params& p, LAS unsigned char* lds, int bh, int rq) {
;     ...
;             for (int tk = 0; tk < TC; ++tk) {
;                 f32x4 nr4 = r4, nd4 = d4, nk4 = k4, na4 = a4, nb4 = b4; float nvv = vv;
;                 if (tk < TC - 1) {
;                     const LAS float* o = ob + (tk + 1) * 6 * 64;
;                     nr4 = *(const LAS f32x4*)(o + cg_ * 4); nd4 = *(const LAS f32x4*)(o + 64 + cg_ * 4); nk4 = *(const LAS f32x4*)(o + 128 + cg_ * 4);
;                     na4 = *(const LAS f32x4*)(o + 256 + cg_ * 4); nb4 = *(const LAS f32x4*)(o + 320 + cg_ * 4);
;                     nvv = o[192 + rq * 16 + rloc];
;                 }
;                 __builtin_amdgcn_sched_barrier(0);
;                 typedef float f32x2_ __attribute__((ext_vector_type(2)));
;                 f32x2_ ta = (f32x2_){S[0], S[1]} * (f32x2_){a4[0], a4[1]}; ta = (f32x2_){S[2], S[3]} * (f32x2_){a4[2], a4[3]} + ta;
;                 f32x2_ ty = (f32x2_){S[0], S[1]} * (f32x2_){rp[0], rp[1]}; ty = (f32x2_){S[2], S[3]} * (f32x2_){rp[2], rp[3]} + ty;
;                 const f32x4 T = S * d4 + vv * k4;
;                 float sa = ta[0] + ta[1];
;                 float yp = ty[0] + ty[1];
;                 sa = dpp_add<0xB1>(sa); yp = dpp_add<0xB1>(yp);
;                 sa = dpp_add<0x4E>(sa); yp = dpp_add<0x4E>(yp);
;                 sa = dpp_add<0x124>(sa); yp = dpp_add<0x124>(yp);
;                 sa = dpp_add<0x128>(sa); yp = dpp_add<0x128>(yp);
;                 if (tk > 0) yk[(tk - 1) >> 4] = (cg_ == ((tk - 1) & 15)) ? yp : yk[(tk - 1) >> 4];
;                 S = sa * b4 + T;
;                 rp = r4;
;                 r4 = nr4; d4 = nd4; k4 = nk4; a4 = na4; b4 = nb4; vv = nvv;
;             }
;             {
;                 float yp = S[0] * rp[0] + S[1] * rp[1] + S[2] * rp[2] + S[3] * rp[3];
;                 yp = row_sum16(yp);
;                 yk[(TC - 1) >> 4] = (cg_ == ((TC - 1) & 15)) ? yp : yk[(TC - 1) >> 4];
;             }
; #pragma unroll
;             for (int j = 0; j < TC / 16; ++j) yk[j] += RKB[buf * TC + j * 16 + cg_] * ob[(j * 16 + cg_) * 6 * 64 + 192 + rq * 16 + rloc];
; #pragma unroll
;             for (int j = 0; j < TC / 16; ++j) YRAW[(size_t)(rowbase + c * TC + j * 16 + cg_) * 512 + h * 64 + rq * 16 + rloc] = yk[j];
	v_add_f32_dpp v161, v206, v206 quad_perm:[1,0,3,2] row_mask:0xf bank_mask:0xf bound_ctrl:1
	v_pk_mul_f32 v[180:181], v[182:183], v[198:199]
	v_add_f32_dpp v160, v160, v160 quad_perm:[1,0,3,2] row_mask:0xf bank_mask:0xf bound_ctrl:1
	v_add_f32_dpp v161, v161, v161 quad_perm:[2,3,0,1] row_mask:0xf bank_mask:0xf bound_ctrl:1
	v_pk_fma_f32 v[180:181], v[186:187], v[200:201], v[180:181] op_sel_hi:[1,0,1]
	v_add_f32_dpp v160, v160, v160 quad_perm:[2,3,0,1] row_mask:0xf bank_mask:0xf bound_ctrl:1
	v_add_f32_dpp v161, v161, v161 row_ror:4 row_mask:0xf bank_mask:0xf bound_ctrl:1
	v_pk_fma_f32 v[162:163], v[184:185], v[200:201], v[162:163] op_sel_hi:[1,0,1]
	v_add_f32_dpp v182, v160, v160 row_ror:4 row_mask:0xf bank_mask:0xf bound_ctrl:1
	v_add_f32_dpp v160, v161, v161 row_ror:8 row_mask:0xf bank_mask:0xf bound_ctrl:1
	v_pk_fma_f32 v[196:197], v[192:193], v[160:161], v[162:163] op_sel_hi:[1,0,1]
	v_add_f32_dpp v161, v182, v182 row_ror:8 row_mask:0xf bank_mask:0xf bound_ctrl:1
	v_cndmask_b32_e64 v31, v31, v161, s[30:31]
	v_pk_fma_f32 v[198:199], v[194:195], v[160:161], v[180:181] op_sel_hi:[1,0,1]
	ds_read_b128 v[160:163], v28 offset:47616
	ds_read_b128 v[180:183], v28 offset:47872
	ds_read_b128 v[184:187], v28 offset:48128
	ds_read_b128 v[188:191], v28 offset:48640
	ds_read_b128 v[192:195], v28 offset:48896
	ds_read_b32 v28, v29 offset:48384
	s_waitcnt lgkmcnt(8)
	v_pk_mul_f32 v[174:175], v[174:175], v[198:199]
	v_pk_mul_f32 v[26:27], v[26:27], v[198:199]
	v_pk_fma_f32 v[172:173], v[172:173], v[196:197], v[174:175]
	v_pk_fma_f32 v[24:25], v[24:25], v[196:197], v[26:27]
	v_add_f32_e32 v29, v172, v173
	v_add_f32_e32 v24, v24, v25
	v_pk_mul_f32 v[26:27], v[164:165], v[196:197]
	v_add_f32_dpp v25, v29, v29 quad_perm:[1,0,3,2] row_mask:0xf bank_mask:0xf bound_ctrl:1
	v_add_f32_dpp v24, v24, v24 quad_perm:[1,0,3,2] row_mask:0xf bank_mask:0xf bound_ctrl:1
	v_pk_mul_f32 v[164:165], v[166:167], v[198:199]
	v_add_f32_dpp v25, v25, v25 quad_perm:[2,3,0,1] row_mask:0xf bank_mask:0xf bound_ctrl:1
	v_add_f32_dpp v24, v24, v24 quad_perm:[2,3,0,1] row_mask:0xf bank_mask:0xf bound_ctrl:1
	s_waitcnt lgkmcnt(6)
	v_pk_fma_f32 v[164:165], v[170:171], v[202:203], v[164:165] op_sel_hi:[1,0,1]
	v_add_f32_dpp v25, v25, v25 row_ror:4 row_mask:0xf bank_mask:0xf bound_ctrl:1
	v_add_f32_dpp v29, v24, v24 row_ror:4 row_mask:0xf bank_mask:0xf bound_ctrl:1
	v_pk_fma_f32 v[26:27], v[168:169], v[202:203], v[26:27] op_sel_hi:[1,0,1]
	v_add_f32_dpp v24, v25, v25 row_ror:8 row_mask:0xf bank_mask:0xf bound_ctrl:1
	v_add_f32_dpp v25, v29, v29 row_ror:8 row_mask:0xf bank_mask:0xf bound_ctrl:1
	v_cndmask_b32_e64 v29, v31, v25, s[34:35]
	v_pk_fma_f32 v[26:27], v[176:177], v[24:25], v[26:27] op_sel_hi:[1,0,1]
	v_pk_fma_f32 v[24:25], v[178:179], v[24:25], v[164:165] op_sel_hi:[1,0,1]
	s_waitcnt lgkmcnt(2)
	v_pk_mul_f32 v[164:165], v[190:191], v[24:25]
	v_pk_mul_f32 v[34:35], v[34:35], v[24:25]
	v_pk_fma_f32 v[164:165], v[188:189], v[26:27], v[164:165]
	v_pk_fma_f32 v[32:33], v[32:33], v[26:27], v[34:35]
	v_pk_mul_f32 v[26:27], v[180:181], v[26:27]
	v_pk_mul_f32 v[24:25], v[182:183], v[24:25]
	s_waitcnt lgkmcnt(0)
	v_pk_fma_f32 v[34:35], v[184:185], v[28:29], v[26:27] op_sel_hi:[1,0,1]
	v_add_f32_e32 v26, v164, v165
	v_add_f32_e32 v27, v32, v33
	v_pk_fma_f32 v[24:25], v[186:187], v[28:29], v[24:25] op_sel_hi:[1,0,1]
	v_add_f32_dpp v26, v26, v26 quad_perm:[1,0,3,2] row_mask:0xf bank_mask:0xf bound_ctrl:1
	v_add_f32_dpp v27, v27, v27 quad_perm:[1,0,3,2] row_mask:0xf bank_mask:0xf bound_ctrl:1
	s_lshl_b32 s79, s94, 2
	v_add_f32_dpp v26, v26, v26 quad_perm:[2,3,0,1] row_mask:0xf bank_mask:0xf bound_ctrl:1
	v_add_f32_dpp v27, v27, v27 quad_perm:[2,3,0,1] row_mask:0xf bank_mask:0xf bound_ctrl:1
	s_add_i32 s79, s79, s78
	v_add_f32_dpp v26, v26, v26 row_ror:4 row_mask:0xf bank_mask:0xf bound_ctrl:1
	v_add_f32_dpp v27, v27, v27 row_ror:4 row_mask:0xf bank_mask:0xf bound_ctrl:1
	v_add3_u32 v32, s79, v135, v84
	v_add_f32_dpp v28, v26, v26 row_ror:8 row_mask:0xf bank_mask:0xf bound_ctrl:1
	v_add_f32_dpp v26, v27, v27 row_ror:8 row_mask:0xf bank_mask:0xf bound_ctrl:1
	v_cndmask_b32_e64 v31, v29, v26, s[36:37]
	v_pk_fma_f32 v[26:27], v[194:195], v[28:29], v[24:25] op_sel_hi:[1,0,1]
	v_pk_fma_f32 v[24:25], v[192:193], v[28:29], v[34:35] op_sel_hi:[1,0,1]
	ds_read2st64_b32 v[32:33], v32 offset0:3 offset1:99
	v_mul_f32_e32 v28, v161, v25
	v_fmac_f32_e32 v28, v160, v24
	v_fmac_f32_e32 v28, v162, v26
	v_fmac_f32_e32 v28, v163, v27
	s_nop 1
	v_add_f32_dpp v34, v28, v28 quad_perm:[1,0,3,2] row_mask:0xf bank_mask:0xf bound_ctrl:1
	v_lshl_add_u32 v28, s95, 7, v126
	ds_read2_b32 v[28:29], v28 offset1:16
	v_add_f32_dpp v34, v34, v34 quad_perm:[2,3,0,1] row_mask:0xf bank_mask:0xf bound_ctrl:1
	s_waitcnt lgkmcnt(0)
	v_fmac_f32_e32 v30, v28, v32
	v_add_f32_dpp v34, v34, v34 row_ror:4 row_mask:0xf bank_mask:0xf bound_ctrl:1
	v_add_u32_e32 v28, s0, v159
	s_nop 0
	v_add_f32_dpp v34, v34, v34 row_ror:8 row_mask:0xf bank_mask:0xf bound_ctrl:1
	v_cndmask_b32_e64 v31, v31, v34, s[4:5]
	v_fmac_f32_e32 v31, v29, v33
	v_ashrrev_i32_e32 v29, 31, v28
	v_lshlrev_b64 v[32:33], 11, v[28:29]
	v_add_u32_e32 v28, 16, v28
	v_ashrrev_i32_e32 v29, 31, v28
	v_lshlrev_b64 v[28:29], 11, v[28:29]
	v_lshl_add_u64 v[32:33], v[88:89], 0, v[32:33]
	v_lshl_add_u64 v[28:29], v[88:89], 0, v[28:29]
	global_store_dword v[32:33], v30, off sc0 sc1
	global_store_dword v[28:29], v31, off sc0 sc1
